# GEMM K loops: adjacent s_setprio 0 / s_setprio 1 pairs between the two MFMA blocks of a super-phase dropped (36 pairs)
# speedup vs baseline: 1.0068x; 1.0068x over previous
.LBB0_226:
	s_add_i32 s24, s4, 2
	s_add_u32 s25, s0, 0x80
	s_addc_u32 s5, s1, 0
	s_add_i32 s48, 0, 0x10000
	s_cmp_eq_u32 s83, s4
	s_cselect_b32 s5, s69, s5
	s_cselect_b32 s4, s68, s25
	s_cselect_b32 s29, s87, s7
	s_cselect_b32 s28, s86, s6
	s_add_i32 s25, 0, 0x14000
	v_add_u32_e32 v150, s48, v174
	v_add_u32_e32 v166, s25, v174
	ds_read_b128 v[128:131], v150
	ds_read_b128 v[132:135], v150 offset:1024
	ds_read_b128 v[146:149], v150 offset:2048
	ds_read_b128 v[150:153], v150 offset:3072
	ds_read_b128 v[154:157], v166
	ds_read_b128 v[158:161], v166 offset:1024
	ds_read_b128 v[162:165], v166 offset:2048
	ds_read_b128 v[166:169], v166 offset:3072
	v_lshl_add_u64 v[170:171], s[0:1], 0, v[142:143]
	s_add_i32 m0, s51, 0xc000
	ds_read_b128 v[176:179], v175
	ds_read_b128 v[180:183], v175 offset:1024
	ds_read_b128 v[184:187], v175 offset:2048
	ds_read_b128 v[188:191], v175 offset:3072
	ds_read_b128 v[218:221], v175 offset:4096
	ds_read_b128 v[222:225], v175 offset:5120
	ds_read_b128 v[226:229], v175 offset:6144
	ds_read_b128 v[230:233], v175 offset:7168
	global_load_lds_dwordx4 v[170:171], off
	v_lshl_add_u64 v[170:171], s[0:1], 0, v[144:145]
	s_add_i32 m0, s51, 0xe000
	s_nop 0
	global_load_lds_dwordx4 v[170:171], off
	s_waitcnt vmcnt(8)
	s_waitcnt lgkmcnt(0)
	s_barrier
	s_setprio 1
	s_waitcnt lgkmcnt(0)
	v_mfma_f32_16x16x32_bf16 v[120:123], v[128:131], v[176:179], v[120:123]
	v_mfma_f32_16x16x32_bf16 v[116:119], v[146:149], v[176:179], v[116:119]
	v_mfma_f32_16x16x32_bf16 v[108:111], v[128:131], v[184:187], v[108:111]
	v_mfma_f32_16x16x32_bf16 v[100:103], v[146:149], v[184:187], v[100:103]
	v_mfma_f32_16x16x32_bf16 v[92:95], v[128:131], v[218:221], v[92:95]
	v_mfma_f32_16x16x32_bf16 v[84:87], v[146:149], v[218:221], v[84:87]
	v_mfma_f32_16x16x32_bf16 v[76:79], v[128:131], v[226:229], v[76:79]
	v_mfma_f32_16x16x32_bf16 v[68:71], v[146:149], v[226:229], v[68:71]
	v_mfma_f32_16x16x32_bf16 v[120:123], v[132:135], v[180:183], v[120:123]
	v_mfma_f32_16x16x32_bf16 v[116:119], v[150:153], v[180:183], v[116:119]
	v_mfma_f32_16x16x32_bf16 v[108:111], v[132:135], v[188:191], v[108:111]
	v_mfma_f32_16x16x32_bf16 v[100:103], v[150:153], v[188:191], v[100:103]
	v_mfma_f32_16x16x32_bf16 v[92:95], v[132:135], v[222:225], v[92:95]
	v_mfma_f32_16x16x32_bf16 v[84:87], v[150:153], v[222:225], v[84:87]
	v_mfma_f32_16x16x32_bf16 v[76:79], v[132:135], v[230:233], v[76:79]
	v_mfma_f32_16x16x32_bf16 v[68:71], v[150:153], v[230:233], v[68:71]
	v_mfma_f32_16x16x32_bf16 v[124:127], v[154:157], v[176:179], v[124:127]
	v_mfma_f32_16x16x32_bf16 v[112:115], v[162:165], v[176:179], v[112:115]
	v_mfma_f32_16x16x32_bf16 v[104:107], v[154:157], v[184:187], v[104:107]
	v_mfma_f32_16x16x32_bf16 v[96:99], v[162:165], v[184:187], v[96:99]
	v_mfma_f32_16x16x32_bf16 v[88:91], v[154:157], v[218:221], v[88:91]
	v_mfma_f32_16x16x32_bf16 v[80:83], v[162:165], v[218:221], v[80:83]
	v_mfma_f32_16x16x32_bf16 v[72:75], v[154:157], v[226:229], v[72:75]
	v_mfma_f32_16x16x32_bf16 v[64:67], v[162:165], v[226:229], v[64:67]
	v_mfma_f32_16x16x32_bf16 v[124:127], v[158:161], v[180:183], v[124:127]
	v_mfma_f32_16x16x32_bf16 v[112:115], v[166:169], v[180:183], v[112:115]
	v_mfma_f32_16x16x32_bf16 v[104:107], v[158:161], v[188:191], v[104:107]
	v_mfma_f32_16x16x32_bf16 v[96:99], v[166:169], v[188:191], v[96:99]
	v_mfma_f32_16x16x32_bf16 v[88:91], v[158:161], v[222:225], v[88:91]
	v_mfma_f32_16x16x32_bf16 v[80:83], v[166:169], v[222:225], v[80:83]
	v_mfma_f32_16x16x32_bf16 v[72:75], v[158:161], v[230:233], v[72:75]
	v_mfma_f32_16x16x32_bf16 v[64:67], v[166:169], v[230:233], v[64:67]
	s_setprio 0
	s_barrier
	s_add_i32 s48, s48, s3
	v_lshl_add_u64 v[170:171], s[28:29], 0, v[194:195]
	s_mov_b32 m0, s48
	ds_read_b128 v[176:179], v175 offset:16384
	ds_read_b128 v[180:183], v175 offset:17408
	ds_read_b128 v[184:187], v175 offset:18432
	ds_read_b128 v[188:191], v175 offset:19456
	ds_read_b128 v[218:221], v175 offset:20480
	ds_read_b128 v[222:225], v175 offset:21504
	ds_read_b128 v[226:229], v175 offset:22528
	ds_read_b128 v[230:233], v175 offset:23552
	global_load_lds_dwordx4 v[170:171], off
	s_add_i32 m0, s48, 0x2000
	v_lshl_add_u64 v[198:199], s[28:29], 0, v[140:141]
	s_add_u32 s28, s28, s8
	s_addc_u32 s29, s29, s9
	s_add_i32 s25, s25, s3
	global_load_lds_dwordx4 v[198:199], off
	v_lshl_add_u64 v[200:201], s[28:29], 0, v[194:195]
	s_mov_b32 m0, s25
	v_lshl_add_u64 v[234:235], s[28:29], 0, v[140:141]
	global_load_lds_dwordx4 v[200:201], off
	s_add_i32 m0, s25, 0x2000
	v_lshl_add_u64 v[236:237], s[4:5], 0, v[136:137]
	global_load_lds_dwordx4 v[234:235], off
	s_mov_b32 m0, s51
	v_lshl_add_u64 v[238:239], s[4:5], 0, v[138:139]
	global_load_lds_dwordx4 v[236:237], off
	s_mov_b32 m0, s54
	s_nop 0
	global_load_lds_dwordx4 v[238:239], off
	s_waitcnt vmcnt(8)
	s_waitcnt lgkmcnt(0)
	s_barrier
	s_setprio 1
	s_waitcnt lgkmcnt(0)
	v_mfma_f32_16x16x32_bf16 v[60:63], v[128:131], v[176:179], v[60:63]
	v_mfma_f32_16x16x32_bf16 v[52:55], v[146:149], v[176:179], v[52:55]
	v_mfma_f32_16x16x32_bf16 v[44:47], v[128:131], v[184:187], v[44:47]
	v_mfma_f32_16x16x32_bf16 v[36:39], v[146:149], v[184:187], v[36:39]
	v_mfma_f32_16x16x32_bf16 v[28:31], v[128:131], v[218:221], v[28:31]
	v_mfma_f32_16x16x32_bf16 v[20:23], v[146:149], v[218:221], v[20:23]
	v_mfma_f32_16x16x32_bf16 v[12:15], v[128:131], v[226:229], v[12:15]
	v_mfma_f32_16x16x32_bf16 v[4:7], v[146:149], v[226:229], v[4:7]
	v_mfma_f32_16x16x32_bf16 v[60:63], v[132:135], v[180:183], v[60:63]
	v_mfma_f32_16x16x32_bf16 v[52:55], v[150:153], v[180:183], v[52:55]
	v_mfma_f32_16x16x32_bf16 v[44:47], v[132:135], v[188:191], v[44:47]
	v_mfma_f32_16x16x32_bf16 v[36:39], v[150:153], v[188:191], v[36:39]
	v_mfma_f32_16x16x32_bf16 v[28:31], v[132:135], v[222:225], v[28:31]
	v_mfma_f32_16x16x32_bf16 v[20:23], v[150:153], v[222:225], v[20:23]
	v_mfma_f32_16x16x32_bf16 v[12:15], v[132:135], v[230:233], v[12:15]
	v_mfma_f32_16x16x32_bf16 v[4:7], v[150:153], v[230:233], v[4:7]
	v_mfma_f32_16x16x32_bf16 v[56:59], v[154:157], v[176:179], v[56:59]
	v_mfma_f32_16x16x32_bf16 v[48:51], v[162:165], v[176:179], v[48:51]
	v_mfma_f32_16x16x32_bf16 v[40:43], v[154:157], v[184:187], v[40:43]
	v_mfma_f32_16x16x32_bf16 v[32:35], v[162:165], v[184:187], v[32:35]
	v_mfma_f32_16x16x32_bf16 v[24:27], v[154:157], v[218:221], v[24:27]
	v_mfma_f32_16x16x32_bf16 v[16:19], v[162:165], v[218:221], v[16:19]
	v_mfma_f32_16x16x32_bf16 v[8:11], v[154:157], v[226:229], v[8:11]
	v_mfma_f32_16x16x32_bf16 v[0:3], v[162:165], v[226:229], v[0:3]
	v_mfma_f32_16x16x32_bf16 v[56:59], v[158:161], v[180:183], v[56:59]
	v_mfma_f32_16x16x32_bf16 v[48:51], v[166:169], v[180:183], v[48:51]
	v_mfma_f32_16x16x32_bf16 v[40:43], v[158:161], v[188:191], v[40:43]
	v_mfma_f32_16x16x32_bf16 v[32:35], v[166:169], v[188:191], v[32:35]
	v_mfma_f32_16x16x32_bf16 v[24:27], v[158:161], v[222:225], v[24:27]
	v_mfma_f32_16x16x32_bf16 v[16:19], v[166:169], v[222:225], v[16:19]
	v_mfma_f32_16x16x32_bf16 v[8:11], v[158:161], v[230:233], v[8:11]
	v_mfma_f32_16x16x32_bf16 v[0:3], v[166:169], v[230:233], v[0:3]
	s_setprio 0
	s_barrier
	s_add_i32 s25, 0, 0x18000
	s_add_i32 s28, 0, 0x1c000
	v_add_u32_e32 v150, s25, v174
	v_add_u32_e32 v166, s28, v174
	ds_read_b128 v[128:131], v150
	ds_read_b128 v[132:135], v150 offset:1024
	ds_read_b128 v[146:149], v150 offset:2048
	ds_read_b128 v[150:153], v150 offset:3072
	ds_read_b128 v[154:157], v166
	ds_read_b128 v[158:161], v166 offset:1024
	ds_read_b128 v[162:165], v166 offset:2048
	ds_read_b128 v[166:169], v166 offset:3072
	s_add_u32 s4, s4, s8
	s_addc_u32 s5, s5, s9
	s_mov_b32 m0, s55
	v_lshl_add_u64 v[240:241], s[4:5], 0, v[136:137]
	ds_read_b128 v[176:179], v175 offset:32768
	ds_read_b128 v[180:183], v175 offset:33792
	ds_read_b128 v[184:187], v175 offset:34816
	ds_read_b128 v[188:191], v175 offset:35840
	ds_read_b128 v[218:221], v175 offset:36864
	ds_read_b128 v[222:225], v175 offset:37888
	ds_read_b128 v[226:229], v175 offset:38912
	ds_read_b128 v[230:233], v175 offset:39936
	global_load_lds_dwordx4 v[240:241], off
	v_lshl_add_u64 v[240:241], s[4:5], 0, v[138:139]
	s_mov_b32 m0, s90
	s_nop 0
	global_load_lds_dwordx4 v[240:241], off
	s_waitcnt vmcnt(8)
	s_waitcnt lgkmcnt(0)
	s_barrier
	s_setprio 1
	s_waitcnt lgkmcnt(0)
	v_mfma_f32_16x16x32_bf16 v[120:123], v[128:131], v[176:179], v[120:123]
	v_mfma_f32_16x16x32_bf16 v[116:119], v[146:149], v[176:179], v[116:119]
	v_mfma_f32_16x16x32_bf16 v[108:111], v[128:131], v[184:187], v[108:111]
	v_mfma_f32_16x16x32_bf16 v[100:103], v[146:149], v[184:187], v[100:103]
	v_mfma_f32_16x16x32_bf16 v[92:95], v[128:131], v[218:221], v[92:95]
	v_mfma_f32_16x16x32_bf16 v[84:87], v[146:149], v[218:221], v[84:87]
	v_mfma_f32_16x16x32_bf16 v[76:79], v[128:131], v[226:229], v[76:79]
	v_mfma_f32_16x16x32_bf16 v[68:71], v[146:149], v[226:229], v[68:71]
	v_mfma_f32_16x16x32_bf16 v[120:123], v[132:135], v[180:183], v[120:123]
	v_mfma_f32_16x16x32_bf16 v[116:119], v[150:153], v[180:183], v[116:119]
	v_mfma_f32_16x16x32_bf16 v[108:111], v[132:135], v[188:191], v[108:111]
	v_mfma_f32_16x16x32_bf16 v[100:103], v[150:153], v[188:191], v[100:103]
	v_mfma_f32_16x16x32_bf16 v[92:95], v[132:135], v[222:225], v[92:95]
	v_mfma_f32_16x16x32_bf16 v[84:87], v[150:153], v[222:225], v[84:87]
	v_mfma_f32_16x16x32_bf16 v[76:79], v[132:135], v[230:233], v[76:79]
	v_mfma_f32_16x16x32_bf16 v[68:71], v[150:153], v[230:233], v[68:71]
	v_mfma_f32_16x16x32_bf16 v[124:127], v[154:157], v[176:179], v[124:127]
	v_mfma_f32_16x16x32_bf16 v[112:115], v[162:165], v[176:179], v[112:115]
	v_mfma_f32_16x16x32_bf16 v[104:107], v[154:157], v[184:187], v[104:107]
	v_mfma_f32_16x16x32_bf16 v[96:99], v[162:165], v[184:187], v[96:99]
	v_mfma_f32_16x16x32_bf16 v[88:91], v[154:157], v[218:221], v[88:91]
	v_mfma_f32_16x16x32_bf16 v[80:83], v[162:165], v[218:221], v[80:83]
	v_mfma_f32_16x16x32_bf16 v[72:75], v[154:157], v[226:229], v[72:75]
	v_mfma_f32_16x16x32_bf16 v[64:67], v[162:165], v[226:229], v[64:67]
	v_mfma_f32_16x16x32_bf16 v[124:127], v[158:161], v[180:183], v[124:127]
	v_mfma_f32_16x16x32_bf16 v[112:115], v[166:169], v[180:183], v[112:115]
	v_mfma_f32_16x16x32_bf16 v[104:107], v[158:161], v[188:191], v[104:107]
	v_mfma_f32_16x16x32_bf16 v[96:99], v[166:169], v[188:191], v[96:99]
	v_mfma_f32_16x16x32_bf16 v[88:91], v[158:161], v[222:225], v[88:91]
	v_mfma_f32_16x16x32_bf16 v[80:83], v[166:169], v[222:225], v[80:83]
	v_mfma_f32_16x16x32_bf16 v[72:75], v[158:161], v[230:233], v[72:75]
	v_mfma_f32_16x16x32_bf16 v[64:67], v[166:169], v[230:233], v[64:67]
	s_setprio 0
	s_barrier
	s_add_i32 s4, s25, s3
	v_lshl_add_u64 v[170:171], v[170:171], 0, s[38:39]
	s_mov_b32 m0, s4
	ds_read_b128 v[176:179], v175 offset:49152
	ds_read_b128 v[180:183], v175 offset:50176
	ds_read_b128 v[184:187], v175 offset:51200
	ds_read_b128 v[188:191], v175 offset:52224
	ds_read_b128 v[218:221], v175 offset:53248
	ds_read_b128 v[222:225], v175 offset:54272
	ds_read_b128 v[226:229], v175 offset:55296
	ds_read_b128 v[230:233], v175 offset:56320
	global_load_lds_dwordx4 v[170:171], off
	v_lshl_add_u64 v[170:171], v[198:199], 0, s[38:39]
	s_add_i32 m0, s4, 0x2000
	s_add_i32 s4, s28, s3
	global_load_lds_dwordx4 v[170:171], off
	v_lshl_add_u64 v[170:171], v[200:201], 0, s[38:39]
	s_mov_b32 m0, s4
	s_nop 0
	global_load_lds_dwordx4 v[170:171], off
	v_lshl_add_u64 v[170:171], v[234:235], 0, s[38:39]
	s_add_i32 m0, s4, 0x2000
	s_nop 0
	global_load_lds_dwordx4 v[170:171], off
	v_lshl_add_u64 v[170:171], v[236:237], 0, s[38:39]
	s_mov_b32 m0, s91
	s_nop 0
	global_load_lds_dwordx4 v[170:171], off
	v_lshl_add_u64 v[170:171], v[238:239], 0, s[38:39]
	s_mov_b32 m0, s82
	s_nop 0
	global_load_lds_dwordx4 v[170:171], off
	s_waitcnt vmcnt(8)
	s_waitcnt lgkmcnt(0)
	s_barrier
	s_setprio 1
	s_waitcnt lgkmcnt(0)
	v_mfma_f32_16x16x32_bf16 v[60:63], v[128:131], v[176:179], v[60:63]
	v_mfma_f32_16x16x32_bf16 v[52:55], v[146:149], v[176:179], v[52:55]
	v_mfma_f32_16x16x32_bf16 v[44:47], v[128:131], v[184:187], v[44:47]
	v_mfma_f32_16x16x32_bf16 v[36:39], v[146:149], v[184:187], v[36:39]
	v_mfma_f32_16x16x32_bf16 v[28:31], v[128:131], v[218:221], v[28:31]
	v_mfma_f32_16x16x32_bf16 v[20:23], v[146:149], v[218:221], v[20:23]
	v_mfma_f32_16x16x32_bf16 v[12:15], v[128:131], v[226:229], v[12:15]
	v_mfma_f32_16x16x32_bf16 v[4:7], v[146:149], v[226:229], v[4:7]
	v_mfma_f32_16x16x32_bf16 v[60:63], v[132:135], v[180:183], v[60:63]
	v_mfma_f32_16x16x32_bf16 v[52:55], v[150:153], v[180:183], v[52:55]
	v_mfma_f32_16x16x32_bf16 v[44:47], v[132:135], v[188:191], v[44:47]
	v_mfma_f32_16x16x32_bf16 v[36:39], v[150:153], v[188:191], v[36:39]
	v_mfma_f32_16x16x32_bf16 v[28:31], v[132:135], v[222:225], v[28:31]
	v_mfma_f32_16x16x32_bf16 v[20:23], v[150:153], v[222:225], v[20:23]
	v_mfma_f32_16x16x32_bf16 v[12:15], v[132:135], v[230:233], v[12:15]
	v_mfma_f32_16x16x32_bf16 v[4:7], v[150:153], v[230:233], v[4:7]
	v_mfma_f32_16x16x32_bf16 v[56:59], v[154:157], v[176:179], v[56:59]
	v_mfma_f32_16x16x32_bf16 v[48:51], v[162:165], v[176:179], v[48:51]
	v_mfma_f32_16x16x32_bf16 v[40:43], v[154:157], v[184:187], v[40:43]
	v_mfma_f32_16x16x32_bf16 v[32:35], v[162:165], v[184:187], v[32:35]
	v_mfma_f32_16x16x32_bf16 v[24:27], v[154:157], v[218:221], v[24:27]
	v_mfma_f32_16x16x32_bf16 v[16:19], v[162:165], v[218:221], v[16:19]
	v_mfma_f32_16x16x32_bf16 v[8:11], v[154:157], v[226:229], v[8:11]
	v_mfma_f32_16x16x32_bf16 v[0:3], v[162:165], v[226:229], v[0:3]
	v_mfma_f32_16x16x32_bf16 v[56:59], v[158:161], v[180:183], v[56:59]
	v_mfma_f32_16x16x32_bf16 v[48:51], v[166:169], v[180:183], v[48:51]
	v_mfma_f32_16x16x32_bf16 v[40:43], v[158:161], v[188:191], v[40:43]
	v_mfma_f32_16x16x32_bf16 v[32:35], v[166:169], v[188:191], v[32:35]
	v_mfma_f32_16x16x32_bf16 v[24:27], v[158:161], v[222:225], v[24:27]
	v_mfma_f32_16x16x32_bf16 v[16:19], v[166:169], v[222:225], v[16:19]
	v_mfma_f32_16x16x32_bf16 v[8:11], v[158:161], v[230:233], v[8:11]
	v_mfma_f32_16x16x32_bf16 v[0:3], v[166:169], v[230:233], v[0:3]
	s_setprio 0
	s_barrier
	s_add_u32 s0, s0, 0x100
	s_addc_u32 s1, s1, 0
	s_add_u32 s6, s6, 0x100
	s_addc_u32 s7, s7, 0
	s_cmp_ge_i32 s24, s16
	s_mov_b32 s4, s24
	s_cbranch_scc0 .LBB0_226

.LBB0_352:
	s_add_i32 s88, s28, 2
	s_add_u32 s89, s24, 0x80
	s_addc_u32 s29, s25, 0
	s_add_i32 s96, 0, 0x10000
	s_cmp_eq_u32 s54, s28
	s_cselect_b32 s29, s19, s29
	s_cselect_b32 s28, s18, s89
	v_add_u32_e32 v142, s96, v146
	s_cselect_b32 s91, s23, s87
	s_cselect_b32 s90, s22, s86
	s_add_i32 s89, 0, 0x14000
	ds_read_b128 v[138:141], v142
	ds_read_b128 v[148:151], v142 offset:1024
	ds_read_b128 v[152:155], v142 offset:2048
	ds_read_b128 v[156:159], v142 offset:3072
	v_add_u32_e32 v142, s89, v146
	ds_read_b128 v[160:163], v142
	ds_read_b128 v[164:167], v142 offset:1024
	ds_read_b128 v[168:171], v142 offset:2048
	ds_read_b128 v[172:175], v142 offset:3072
	v_lshl_add_u64 v[142:143], s[24:25], 0, v[134:135]
	s_add_i32 m0, s31, 0xc000
	ds_read_b128 v[176:179], v147
	ds_read_b128 v[180:183], v147 offset:1024
	ds_read_b128 v[184:187], v147 offset:2048
	ds_read_b128 v[188:191], v147 offset:3072
	ds_read_b128 v[218:221], v147 offset:4096
	ds_read_b128 v[222:225], v147 offset:5120
	ds_read_b128 v[226:229], v147 offset:6144
	ds_read_b128 v[230:233], v147 offset:7168
	global_load_lds_dwordx4 v[142:143], off
	v_lshl_add_u64 v[142:143], s[24:25], 0, v[136:137]
	s_add_i32 m0, s31, 0xe000
	s_nop 0
	global_load_lds_dwordx4 v[142:143], off
	s_waitcnt vmcnt(8)
	s_waitcnt lgkmcnt(0)
	s_barrier
	s_setprio 1
	s_waitcnt lgkmcnt(0)
	v_mfma_f32_16x16x32_bf16 v[124:127], v[138:141], v[176:179], v[124:127]
	v_mfma_f32_16x16x32_bf16 v[120:123], v[152:155], v[176:179], v[120:123]
	v_mfma_f32_16x16x32_bf16 v[108:111], v[138:141], v[184:187], v[108:111]
	v_mfma_f32_16x16x32_bf16 v[104:107], v[152:155], v[184:187], v[104:107]
	v_mfma_f32_16x16x32_bf16 v[92:95], v[138:141], v[218:221], v[92:95]
	v_mfma_f32_16x16x32_bf16 v[88:91], v[152:155], v[218:221], v[88:91]
	v_mfma_f32_16x16x32_bf16 v[76:79], v[138:141], v[226:229], v[76:79]
	v_mfma_f32_16x16x32_bf16 v[72:75], v[152:155], v[226:229], v[72:75]
	v_mfma_f32_16x16x32_bf16 v[124:127], v[148:151], v[180:183], v[124:127]
	v_mfma_f32_16x16x32_bf16 v[120:123], v[156:159], v[180:183], v[120:123]
	v_mfma_f32_16x16x32_bf16 v[108:111], v[148:151], v[188:191], v[108:111]
	v_mfma_f32_16x16x32_bf16 v[104:107], v[156:159], v[188:191], v[104:107]
	v_mfma_f32_16x16x32_bf16 v[92:95], v[148:151], v[222:225], v[92:95]
	v_mfma_f32_16x16x32_bf16 v[88:91], v[156:159], v[222:225], v[88:91]
	v_mfma_f32_16x16x32_bf16 v[76:79], v[148:151], v[230:233], v[76:79]
	v_mfma_f32_16x16x32_bf16 v[72:75], v[156:159], v[230:233], v[72:75]
	v_mfma_f32_16x16x32_bf16 v[116:119], v[160:163], v[176:179], v[116:119]
	v_mfma_f32_16x16x32_bf16 v[112:115], v[168:171], v[176:179], v[112:115]
	v_mfma_f32_16x16x32_bf16 v[100:103], v[160:163], v[184:187], v[100:103]
	v_mfma_f32_16x16x32_bf16 v[96:99], v[168:171], v[184:187], v[96:99]
	v_mfma_f32_16x16x32_bf16 v[84:87], v[160:163], v[218:221], v[84:87]
	v_mfma_f32_16x16x32_bf16 v[80:83], v[168:171], v[218:221], v[80:83]
	v_mfma_f32_16x16x32_bf16 v[68:71], v[160:163], v[226:229], v[68:71]
	v_mfma_f32_16x16x32_bf16 v[64:67], v[168:171], v[226:229], v[64:67]
	v_mfma_f32_16x16x32_bf16 v[116:119], v[164:167], v[180:183], v[116:119]
	v_mfma_f32_16x16x32_bf16 v[112:115], v[172:175], v[180:183], v[112:115]
	v_mfma_f32_16x16x32_bf16 v[100:103], v[164:167], v[188:191], v[100:103]
	v_mfma_f32_16x16x32_bf16 v[96:99], v[172:175], v[188:191], v[96:99]
	v_mfma_f32_16x16x32_bf16 v[84:87], v[164:167], v[222:225], v[84:87]
	v_mfma_f32_16x16x32_bf16 v[80:83], v[172:175], v[222:225], v[80:83]
	v_mfma_f32_16x16x32_bf16 v[68:71], v[164:167], v[230:233], v[68:71]
	v_mfma_f32_16x16x32_bf16 v[64:67], v[172:175], v[230:233], v[64:67]
	s_setprio 0
	s_barrier
	s_add_i32 s96, s96, s30
	v_lshl_add_u64 v[142:143], s[90:91], 0, v[194:195]
	s_mov_b32 m0, s96
	ds_read_b128 v[176:179], v147 offset:16384
	ds_read_b128 v[180:183], v147 offset:17408
	ds_read_b128 v[184:187], v147 offset:18432
	ds_read_b128 v[188:191], v147 offset:19456
	ds_read_b128 v[218:221], v147 offset:20480
	ds_read_b128 v[222:225], v147 offset:21504
	ds_read_b128 v[226:229], v147 offset:22528
	ds_read_b128 v[230:233], v147 offset:23552
	global_load_lds_dwordx4 v[142:143], off
	s_add_i32 m0, s96, 0x2000
	v_lshl_add_u64 v[198:199], s[90:91], 0, v[132:133]
	s_add_u32 s90, s90, s4
	s_addc_u32 s91, s91, s5
	s_add_i32 s89, s89, s30
	global_load_lds_dwordx4 v[198:199], off
	v_lshl_add_u64 v[200:201], s[90:91], 0, v[194:195]
	s_mov_b32 m0, s89
	v_lshl_add_u64 v[234:235], s[90:91], 0, v[132:133]
	global_load_lds_dwordx4 v[200:201], off
	s_add_i32 m0, s89, 0x2000
	v_lshl_add_u64 v[236:237], s[28:29], 0, v[128:129]
	global_load_lds_dwordx4 v[234:235], off
	s_mov_b32 m0, s31
	v_lshl_add_u64 v[238:239], s[28:29], 0, v[130:131]
	global_load_lds_dwordx4 v[236:237], off
	s_mov_b32 m0, s33
	s_nop 0
	global_load_lds_dwordx4 v[238:239], off
	s_waitcnt vmcnt(8)
	s_waitcnt lgkmcnt(0)
	s_barrier
	s_setprio 1
	s_waitcnt lgkmcnt(0)
	v_mfma_f32_16x16x32_bf16 v[60:63], v[138:141], v[176:179], v[60:63]
	v_mfma_f32_16x16x32_bf16 v[56:59], v[152:155], v[176:179], v[56:59]
	v_mfma_f32_16x16x32_bf16 v[44:47], v[138:141], v[184:187], v[44:47]
	v_mfma_f32_16x16x32_bf16 v[40:43], v[152:155], v[184:187], v[40:43]
	v_mfma_f32_16x16x32_bf16 v[28:31], v[138:141], v[218:221], v[28:31]
	v_mfma_f32_16x16x32_bf16 v[24:27], v[152:155], v[218:221], v[24:27]
	v_mfma_f32_16x16x32_bf16 v[12:15], v[138:141], v[226:229], v[12:15]
	v_mfma_f32_16x16x32_bf16 v[8:11], v[152:155], v[226:229], v[8:11]
	v_mfma_f32_16x16x32_bf16 v[60:63], v[148:151], v[180:183], v[60:63]
	v_mfma_f32_16x16x32_bf16 v[56:59], v[156:159], v[180:183], v[56:59]
	v_mfma_f32_16x16x32_bf16 v[44:47], v[148:151], v[188:191], v[44:47]
	v_mfma_f32_16x16x32_bf16 v[40:43], v[156:159], v[188:191], v[40:43]
	v_mfma_f32_16x16x32_bf16 v[28:31], v[148:151], v[222:225], v[28:31]
	v_mfma_f32_16x16x32_bf16 v[24:27], v[156:159], v[222:225], v[24:27]
	v_mfma_f32_16x16x32_bf16 v[12:15], v[148:151], v[230:233], v[12:15]
	v_mfma_f32_16x16x32_bf16 v[8:11], v[156:159], v[230:233], v[8:11]
	v_mfma_f32_16x16x32_bf16 v[52:55], v[160:163], v[176:179], v[52:55]
	v_mfma_f32_16x16x32_bf16 v[48:51], v[168:171], v[176:179], v[48:51]
	v_mfma_f32_16x16x32_bf16 v[36:39], v[160:163], v[184:187], v[36:39]
	v_mfma_f32_16x16x32_bf16 v[32:35], v[168:171], v[184:187], v[32:35]
	v_mfma_f32_16x16x32_bf16 v[20:23], v[160:163], v[218:221], v[20:23]
	v_mfma_f32_16x16x32_bf16 v[16:19], v[168:171], v[218:221], v[16:19]
	v_mfma_f32_16x16x32_bf16 v[4:7], v[160:163], v[226:229], v[4:7]
	v_mfma_f32_16x16x32_bf16 v[0:3], v[168:171], v[226:229], v[0:3]
	v_mfma_f32_16x16x32_bf16 v[52:55], v[164:167], v[180:183], v[52:55]
	v_mfma_f32_16x16x32_bf16 v[48:51], v[172:175], v[180:183], v[48:51]
	v_mfma_f32_16x16x32_bf16 v[36:39], v[164:167], v[188:191], v[36:39]
	v_mfma_f32_16x16x32_bf16 v[32:35], v[172:175], v[188:191], v[32:35]
	v_mfma_f32_16x16x32_bf16 v[20:23], v[164:167], v[222:225], v[20:23]
	v_mfma_f32_16x16x32_bf16 v[16:19], v[172:175], v[222:225], v[16:19]
	v_mfma_f32_16x16x32_bf16 v[4:7], v[164:167], v[230:233], v[4:7]
	v_mfma_f32_16x16x32_bf16 v[0:3], v[172:175], v[230:233], v[0:3]
	s_setprio 0
	s_barrier
	s_add_i32 s89, 0, 0x18000
	s_add_i32 s90, 0, 0x1c000
	v_add_u32_e32 v156, s89, v146
	v_add_u32_e32 v172, s90, v146
	ds_read_b128 v[138:141], v156
	ds_read_b128 v[148:151], v156 offset:1024
	ds_read_b128 v[152:155], v156 offset:2048
	ds_read_b128 v[156:159], v156 offset:3072
	ds_read_b128 v[160:163], v172
	ds_read_b128 v[164:167], v172 offset:1024
	ds_read_b128 v[168:171], v172 offset:2048
	ds_read_b128 v[172:175], v172 offset:3072
	s_add_u32 s28, s28, s4
	s_addc_u32 s29, s29, s5
	s_mov_b32 m0, s35
	v_lshl_add_u64 v[240:241], s[28:29], 0, v[128:129]
	ds_read_b128 v[176:179], v147 offset:32768
	ds_read_b128 v[180:183], v147 offset:33792
	ds_read_b128 v[184:187], v147 offset:34816
	ds_read_b128 v[188:191], v147 offset:35840
	ds_read_b128 v[218:221], v147 offset:36864
	ds_read_b128 v[222:225], v147 offset:37888
	ds_read_b128 v[226:229], v147 offset:38912
	ds_read_b128 v[230:233], v147 offset:39936
	global_load_lds_dwordx4 v[240:241], off
	v_lshl_add_u64 v[240:241], s[28:29], 0, v[130:131]
	s_mov_b32 m0, s42
	s_nop 0
	global_load_lds_dwordx4 v[240:241], off
	s_waitcnt vmcnt(8)
	s_waitcnt lgkmcnt(0)
	s_barrier
	s_setprio 1
	s_waitcnt lgkmcnt(0)
	v_mfma_f32_16x16x32_bf16 v[124:127], v[138:141], v[176:179], v[124:127]
	v_mfma_f32_16x16x32_bf16 v[120:123], v[152:155], v[176:179], v[120:123]
	v_mfma_f32_16x16x32_bf16 v[108:111], v[138:141], v[184:187], v[108:111]
	v_mfma_f32_16x16x32_bf16 v[104:107], v[152:155], v[184:187], v[104:107]
	v_mfma_f32_16x16x32_bf16 v[92:95], v[138:141], v[218:221], v[92:95]
	v_mfma_f32_16x16x32_bf16 v[88:91], v[152:155], v[218:221], v[88:91]
	v_mfma_f32_16x16x32_bf16 v[76:79], v[138:141], v[226:229], v[76:79]
	v_mfma_f32_16x16x32_bf16 v[72:75], v[152:155], v[226:229], v[72:75]
	v_mfma_f32_16x16x32_bf16 v[124:127], v[148:151], v[180:183], v[124:127]
	v_mfma_f32_16x16x32_bf16 v[120:123], v[156:159], v[180:183], v[120:123]
	v_mfma_f32_16x16x32_bf16 v[108:111], v[148:151], v[188:191], v[108:111]
	v_mfma_f32_16x16x32_bf16 v[104:107], v[156:159], v[188:191], v[104:107]
	v_mfma_f32_16x16x32_bf16 v[92:95], v[148:151], v[222:225], v[92:95]
	v_mfma_f32_16x16x32_bf16 v[88:91], v[156:159], v[222:225], v[88:91]
	v_mfma_f32_16x16x32_bf16 v[76:79], v[148:151], v[230:233], v[76:79]
	v_mfma_f32_16x16x32_bf16 v[72:75], v[156:159], v[230:233], v[72:75]
	v_mfma_f32_16x16x32_bf16 v[116:119], v[160:163], v[176:179], v[116:119]
	v_mfma_f32_16x16x32_bf16 v[112:115], v[168:171], v[176:179], v[112:115]
	v_mfma_f32_16x16x32_bf16 v[100:103], v[160:163], v[184:187], v[100:103]
	v_mfma_f32_16x16x32_bf16 v[96:99], v[168:171], v[184:187], v[96:99]
	v_mfma_f32_16x16x32_bf16 v[84:87], v[160:163], v[218:221], v[84:87]
	v_mfma_f32_16x16x32_bf16 v[80:83], v[168:171], v[218:221], v[80:83]
	v_mfma_f32_16x16x32_bf16 v[68:71], v[160:163], v[226:229], v[68:71]
	v_mfma_f32_16x16x32_bf16 v[64:67], v[168:171], v[226:229], v[64:67]
	v_mfma_f32_16x16x32_bf16 v[116:119], v[164:167], v[180:183], v[116:119]
	v_mfma_f32_16x16x32_bf16 v[112:115], v[172:175], v[180:183], v[112:115]
	v_mfma_f32_16x16x32_bf16 v[100:103], v[164:167], v[188:191], v[100:103]
	v_mfma_f32_16x16x32_bf16 v[96:99], v[172:175], v[188:191], v[96:99]
	v_mfma_f32_16x16x32_bf16 v[84:87], v[164:167], v[222:225], v[84:87]
	v_mfma_f32_16x16x32_bf16 v[80:83], v[172:175], v[222:225], v[80:83]
	v_mfma_f32_16x16x32_bf16 v[68:71], v[164:167], v[230:233], v[68:71]
	v_mfma_f32_16x16x32_bf16 v[64:67], v[172:175], v[230:233], v[64:67]
	s_setprio 0
	s_barrier
	s_add_i32 s28, s89, s30
	v_lshl_add_u64 v[142:143], v[142:143], 0, s[38:39]
	s_mov_b32 m0, s28
	ds_read_b128 v[176:179], v147 offset:49152
	ds_read_b128 v[180:183], v147 offset:50176
	ds_read_b128 v[184:187], v147 offset:51200
	ds_read_b128 v[188:191], v147 offset:52224
	ds_read_b128 v[218:221], v147 offset:53248
	ds_read_b128 v[222:225], v147 offset:54272
	ds_read_b128 v[226:229], v147 offset:55296
	ds_read_b128 v[230:233], v147 offset:56320
	global_load_lds_dwordx4 v[142:143], off
	v_lshl_add_u64 v[142:143], v[198:199], 0, s[38:39]
	s_add_i32 m0, s28, 0x2000
	s_add_i32 s28, s90, s30
	global_load_lds_dwordx4 v[142:143], off
	v_lshl_add_u64 v[142:143], v[200:201], 0, s[38:39]
	s_mov_b32 m0, s28
	s_nop 0
	global_load_lds_dwordx4 v[142:143], off
	v_lshl_add_u64 v[142:143], v[234:235], 0, s[38:39]
	s_add_i32 m0, s28, 0x2000
	s_nop 0
	global_load_lds_dwordx4 v[142:143], off
	v_lshl_add_u64 v[142:143], v[236:237], 0, s[38:39]
	s_mov_b32 m0, s50
	s_nop 0
	global_load_lds_dwordx4 v[142:143], off
	v_lshl_add_u64 v[142:143], v[238:239], 0, s[38:39]
	s_mov_b32 m0, s51
	s_nop 0
	global_load_lds_dwordx4 v[142:143], off
	s_waitcnt vmcnt(8)
	s_waitcnt lgkmcnt(0)
	s_barrier
	s_setprio 1
	s_waitcnt lgkmcnt(0)
	v_mfma_f32_16x16x32_bf16 v[60:63], v[138:141], v[176:179], v[60:63]
	v_mfma_f32_16x16x32_bf16 v[56:59], v[152:155], v[176:179], v[56:59]
	v_mfma_f32_16x16x32_bf16 v[44:47], v[138:141], v[184:187], v[44:47]
	v_mfma_f32_16x16x32_bf16 v[40:43], v[152:155], v[184:187], v[40:43]
	v_mfma_f32_16x16x32_bf16 v[28:31], v[138:141], v[218:221], v[28:31]
	v_mfma_f32_16x16x32_bf16 v[24:27], v[152:155], v[218:221], v[24:27]
	v_mfma_f32_16x16x32_bf16 v[12:15], v[138:141], v[226:229], v[12:15]
	v_mfma_f32_16x16x32_bf16 v[8:11], v[152:155], v[226:229], v[8:11]
	v_mfma_f32_16x16x32_bf16 v[60:63], v[148:151], v[180:183], v[60:63]
	v_mfma_f32_16x16x32_bf16 v[56:59], v[156:159], v[180:183], v[56:59]
	v_mfma_f32_16x16x32_bf16 v[44:47], v[148:151], v[188:191], v[44:47]
	v_mfma_f32_16x16x32_bf16 v[40:43], v[156:159], v[188:191], v[40:43]
	v_mfma_f32_16x16x32_bf16 v[28:31], v[148:151], v[222:225], v[28:31]
	v_mfma_f32_16x16x32_bf16 v[24:27], v[156:159], v[222:225], v[24:27]
	v_mfma_f32_16x16x32_bf16 v[12:15], v[148:151], v[230:233], v[12:15]
	v_mfma_f32_16x16x32_bf16 v[8:11], v[156:159], v[230:233], v[8:11]
	v_mfma_f32_16x16x32_bf16 v[52:55], v[160:163], v[176:179], v[52:55]
	v_mfma_f32_16x16x32_bf16 v[48:51], v[168:171], v[176:179], v[48:51]
	v_mfma_f32_16x16x32_bf16 v[36:39], v[160:163], v[184:187], v[36:39]
	v_mfma_f32_16x16x32_bf16 v[32:35], v[168:171], v[184:187], v[32:35]
	v_mfma_f32_16x16x32_bf16 v[20:23], v[160:163], v[218:221], v[20:23]
	v_mfma_f32_16x16x32_bf16 v[16:19], v[168:171], v[218:221], v[16:19]
	v_mfma_f32_16x16x32_bf16 v[4:7], v[160:163], v[226:229], v[4:7]
	v_mfma_f32_16x16x32_bf16 v[0:3], v[168:171], v[226:229], v[0:3]
	v_mfma_f32_16x16x32_bf16 v[52:55], v[164:167], v[180:183], v[52:55]
	v_mfma_f32_16x16x32_bf16 v[48:51], v[172:175], v[180:183], v[48:51]
	v_mfma_f32_16x16x32_bf16 v[36:39], v[164:167], v[188:191], v[36:39]
	v_mfma_f32_16x16x32_bf16 v[32:35], v[172:175], v[188:191], v[32:35]
	v_mfma_f32_16x16x32_bf16 v[20:23], v[164:167], v[222:225], v[20:23]
	v_mfma_f32_16x16x32_bf16 v[16:19], v[172:175], v[222:225], v[16:19]
	v_mfma_f32_16x16x32_bf16 v[4:7], v[164:167], v[230:233], v[4:7]
	v_mfma_f32_16x16x32_bf16 v[0:3], v[172:175], v[230:233], v[0:3]
	s_setprio 0
	s_barrier
	s_add_u32 s24, s24, 0x100
	s_addc_u32 s25, s25, 0
	s_add_u32 s86, s86, 0x100
	s_addc_u32 s87, s87, 0
	s_cmp_ge_i32 s88, s43
	s_mov_b32 s28, s88
	s_cbranch_scc0 .LBB0_352

.LBB0_571:
	s_add_i32 s72, s28, 2
	s_add_u32 s73, s24, 0x80
	s_addc_u32 s29, s25, 0
	s_add_i32 s86, 0, 0x10000
	s_cmp_eq_u32 s48, s28
	s_cselect_b32 s29, s5, s29
	s_cselect_b32 s28, s4, s73
	s_cselect_b32 s83, s23, s69
	s_cselect_b32 s82, s22, s68
	s_add_i32 s73, 0, 0x14000
	v_add_u32_e32 v140, s86, v168
	v_add_u32_e32 v170, s73, v168
	ds_read_b128 v[128:131], v140
	ds_read_b128 v[132:135], v140 offset:1024
	ds_read_b128 v[136:139], v140 offset:2048
	ds_read_b128 v[140:143], v140 offset:3072
	ds_read_b128 v[154:157], v170
	ds_read_b128 v[158:161], v170 offset:1024
	ds_read_b128 v[162:165], v170 offset:2048
	ds_read_b128 v[170:173], v170 offset:3072
	v_lshl_add_u64 v[190:191], s[24:25], 0, v[150:151]
	s_add_i32 m0, s6, 0xc000
	ds_read_b128 v[174:177], v169
	ds_read_b128 v[178:181], v169 offset:1024
	ds_read_b128 v[182:185], v169 offset:2048
	ds_read_b128 v[186:189], v169 offset:3072
	ds_read_b128 v[218:221], v169 offset:4096
	ds_read_b128 v[222:225], v169 offset:5120
	ds_read_b128 v[226:229], v169 offset:6144
	ds_read_b128 v[230:233], v169 offset:7168
	global_load_lds_dwordx4 v[190:191], off
	v_lshl_add_u64 v[190:191], s[24:25], 0, v[152:153]
	s_add_i32 m0, s6, 0xe000
	s_nop 0
	global_load_lds_dwordx4 v[190:191], off
	s_waitcnt vmcnt(8)
	s_waitcnt lgkmcnt(0)
	s_barrier
	s_setprio 1
	s_waitcnt lgkmcnt(0)
	v_mfma_f32_16x16x32_bf16 v[120:123], v[128:131], v[174:177], v[120:123]
	v_mfma_f32_16x16x32_bf16 v[124:127], v[136:139], v[174:177], v[124:127]
	v_mfma_f32_16x16x32_bf16 v[108:111], v[128:131], v[182:185], v[108:111]
	v_mfma_f32_16x16x32_bf16 v[104:107], v[136:139], v[182:185], v[104:107]
	v_mfma_f32_16x16x32_bf16 v[92:95], v[128:131], v[218:221], v[92:95]
	v_mfma_f32_16x16x32_bf16 v[88:91], v[136:139], v[218:221], v[88:91]
	v_mfma_f32_16x16x32_bf16 v[76:79], v[128:131], v[226:229], v[76:79]
	v_mfma_f32_16x16x32_bf16 v[72:75], v[136:139], v[226:229], v[72:75]
	v_mfma_f32_16x16x32_bf16 v[120:123], v[132:135], v[178:181], v[120:123]
	v_mfma_f32_16x16x32_bf16 v[124:127], v[140:143], v[178:181], v[124:127]
	v_mfma_f32_16x16x32_bf16 v[108:111], v[132:135], v[186:189], v[108:111]
	v_mfma_f32_16x16x32_bf16 v[104:107], v[140:143], v[186:189], v[104:107]
	v_mfma_f32_16x16x32_bf16 v[92:95], v[132:135], v[222:225], v[92:95]
	v_mfma_f32_16x16x32_bf16 v[88:91], v[140:143], v[222:225], v[88:91]
	v_mfma_f32_16x16x32_bf16 v[76:79], v[132:135], v[230:233], v[76:79]
	v_mfma_f32_16x16x32_bf16 v[72:75], v[140:143], v[230:233], v[72:75]
	v_mfma_f32_16x16x32_bf16 v[116:119], v[154:157], v[174:177], v[116:119]
	v_mfma_f32_16x16x32_bf16 v[112:115], v[162:165], v[174:177], v[112:115]
	v_mfma_f32_16x16x32_bf16 v[100:103], v[154:157], v[182:185], v[100:103]
	v_mfma_f32_16x16x32_bf16 v[96:99], v[162:165], v[182:185], v[96:99]
	v_mfma_f32_16x16x32_bf16 v[84:87], v[154:157], v[218:221], v[84:87]
	v_mfma_f32_16x16x32_bf16 v[80:83], v[162:165], v[218:221], v[80:83]
	v_mfma_f32_16x16x32_bf16 v[68:71], v[154:157], v[226:229], v[68:71]
	v_mfma_f32_16x16x32_bf16 v[64:67], v[162:165], v[226:229], v[64:67]
	v_mfma_f32_16x16x32_bf16 v[116:119], v[158:161], v[178:181], v[116:119]
	v_mfma_f32_16x16x32_bf16 v[112:115], v[170:173], v[178:181], v[112:115]
	v_mfma_f32_16x16x32_bf16 v[100:103], v[158:161], v[186:189], v[100:103]
	v_mfma_f32_16x16x32_bf16 v[96:99], v[170:173], v[186:189], v[96:99]
	v_mfma_f32_16x16x32_bf16 v[84:87], v[158:161], v[222:225], v[84:87]
	v_mfma_f32_16x16x32_bf16 v[80:83], v[170:173], v[222:225], v[80:83]
	v_mfma_f32_16x16x32_bf16 v[68:71], v[158:161], v[230:233], v[68:71]
	v_mfma_f32_16x16x32_bf16 v[64:67], v[170:173], v[230:233], v[64:67]
	s_setprio 0
	s_barrier
	s_add_i32 s86, s86, s3
	v_lshl_add_u64 v[190:191], s[82:83], 0, v[194:195]
	s_mov_b32 m0, s86
	ds_read_b128 v[174:177], v169 offset:16384
	ds_read_b128 v[178:181], v169 offset:17408
	ds_read_b128 v[182:185], v169 offset:18432
	ds_read_b128 v[186:189], v169 offset:19456
	ds_read_b128 v[218:221], v169 offset:20480
	ds_read_b128 v[222:225], v169 offset:21504
	ds_read_b128 v[226:229], v169 offset:22528
	ds_read_b128 v[230:233], v169 offset:23552
	global_load_lds_dwordx4 v[190:191], off
	s_add_i32 m0, s86, 0x2000
	v_lshl_add_u64 v[198:199], s[82:83], 0, v[144:145]
	s_add_u32 s82, s82, s8
	s_addc_u32 s83, s83, s9
	s_add_i32 s73, s73, s3
	global_load_lds_dwordx4 v[198:199], off
	v_lshl_add_u64 v[200:201], s[82:83], 0, v[194:195]
	s_mov_b32 m0, s73
	v_lshl_add_u64 v[234:235], s[82:83], 0, v[144:145]
	global_load_lds_dwordx4 v[200:201], off
	s_add_i32 m0, s73, 0x2000
	v_lshl_add_u64 v[236:237], s[28:29], 0, v[148:149]
	global_load_lds_dwordx4 v[234:235], off
	s_mov_b32 m0, s6
	v_lshl_add_u64 v[238:239], s[28:29], 0, v[146:147]
	global_load_lds_dwordx4 v[236:237], off
	s_mov_b32 m0, s7
	s_nop 0
	global_load_lds_dwordx4 v[238:239], off
	s_waitcnt vmcnt(8)
	s_waitcnt lgkmcnt(0)
	s_barrier
	s_setprio 1
	s_waitcnt lgkmcnt(0)
	v_mfma_f32_16x16x32_bf16 v[60:63], v[128:131], v[174:177], v[60:63]
	v_mfma_f32_16x16x32_bf16 v[56:59], v[136:139], v[174:177], v[56:59]
	v_mfma_f32_16x16x32_bf16 v[44:47], v[128:131], v[182:185], v[44:47]
	v_mfma_f32_16x16x32_bf16 v[40:43], v[136:139], v[182:185], v[40:43]
	v_mfma_f32_16x16x32_bf16 v[28:31], v[128:131], v[218:221], v[28:31]
	v_mfma_f32_16x16x32_bf16 v[24:27], v[136:139], v[218:221], v[24:27]
	v_mfma_f32_16x16x32_bf16 v[12:15], v[128:131], v[226:229], v[12:15]
	v_mfma_f32_16x16x32_bf16 v[8:11], v[136:139], v[226:229], v[8:11]
	v_mfma_f32_16x16x32_bf16 v[60:63], v[132:135], v[178:181], v[60:63]
	v_mfma_f32_16x16x32_bf16 v[56:59], v[140:143], v[178:181], v[56:59]
	v_mfma_f32_16x16x32_bf16 v[44:47], v[132:135], v[186:189], v[44:47]
	v_mfma_f32_16x16x32_bf16 v[40:43], v[140:143], v[186:189], v[40:43]
	v_mfma_f32_16x16x32_bf16 v[28:31], v[132:135], v[222:225], v[28:31]
	v_mfma_f32_16x16x32_bf16 v[24:27], v[140:143], v[222:225], v[24:27]
	v_mfma_f32_16x16x32_bf16 v[12:15], v[132:135], v[230:233], v[12:15]
	v_mfma_f32_16x16x32_bf16 v[8:11], v[140:143], v[230:233], v[8:11]
	v_mfma_f32_16x16x32_bf16 v[52:55], v[154:157], v[174:177], v[52:55]
	v_mfma_f32_16x16x32_bf16 v[48:51], v[162:165], v[174:177], v[48:51]
	v_mfma_f32_16x16x32_bf16 v[36:39], v[154:157], v[182:185], v[36:39]
	v_mfma_f32_16x16x32_bf16 v[32:35], v[162:165], v[182:185], v[32:35]
	v_mfma_f32_16x16x32_bf16 v[20:23], v[154:157], v[218:221], v[20:23]
	v_mfma_f32_16x16x32_bf16 v[16:19], v[162:165], v[218:221], v[16:19]
	v_mfma_f32_16x16x32_bf16 v[4:7], v[154:157], v[226:229], v[4:7]
	v_mfma_f32_16x16x32_bf16 v[0:3], v[162:165], v[226:229], v[0:3]
	v_mfma_f32_16x16x32_bf16 v[52:55], v[158:161], v[178:181], v[52:55]
	v_mfma_f32_16x16x32_bf16 v[48:51], v[170:173], v[178:181], v[48:51]
	v_mfma_f32_16x16x32_bf16 v[36:39], v[158:161], v[186:189], v[36:39]
	v_mfma_f32_16x16x32_bf16 v[32:35], v[170:173], v[186:189], v[32:35]
	v_mfma_f32_16x16x32_bf16 v[20:23], v[158:161], v[222:225], v[20:23]
	v_mfma_f32_16x16x32_bf16 v[16:19], v[170:173], v[222:225], v[16:19]
	v_mfma_f32_16x16x32_bf16 v[4:7], v[158:161], v[230:233], v[4:7]
	v_mfma_f32_16x16x32_bf16 v[0:3], v[170:173], v[230:233], v[0:3]
	s_setprio 0
	s_barrier
	s_add_i32 s73, 0, 0x18000
	s_add_i32 s82, 0, 0x1c000
	v_add_u32_e32 v140, s73, v168
	v_add_u32_e32 v170, s82, v168
	ds_read_b128 v[128:131], v140
	ds_read_b128 v[132:135], v140 offset:1024
	ds_read_b128 v[136:139], v140 offset:2048
	ds_read_b128 v[140:143], v140 offset:3072
	ds_read_b128 v[154:157], v170
	ds_read_b128 v[158:161], v170 offset:1024
	ds_read_b128 v[162:165], v170 offset:2048
	ds_read_b128 v[170:173], v170 offset:3072
	s_add_u32 s28, s28, s8
	s_addc_u32 s29, s29, s9
	s_mov_b32 m0, s16
	v_lshl_add_u64 v[240:241], s[28:29], 0, v[148:149]
	ds_read_b128 v[174:177], v169 offset:32768
	ds_read_b128 v[178:181], v169 offset:33792
	ds_read_b128 v[182:185], v169 offset:34816
	ds_read_b128 v[186:189], v169 offset:35840
	ds_read_b128 v[218:221], v169 offset:36864
	ds_read_b128 v[222:225], v169 offset:37888
	ds_read_b128 v[226:229], v169 offset:38912
	ds_read_b128 v[230:233], v169 offset:39936
	global_load_lds_dwordx4 v[240:241], off
	v_lshl_add_u64 v[240:241], s[28:29], 0, v[146:147]
	s_mov_b32 m0, s20
	s_nop 0
	global_load_lds_dwordx4 v[240:241], off
	s_waitcnt vmcnt(8)
	s_waitcnt lgkmcnt(0)
	s_barrier
	s_setprio 1
	s_waitcnt lgkmcnt(0)
	v_mfma_f32_16x16x32_bf16 v[120:123], v[128:131], v[174:177], v[120:123]
	v_mfma_f32_16x16x32_bf16 v[124:127], v[136:139], v[174:177], v[124:127]
	v_mfma_f32_16x16x32_bf16 v[108:111], v[128:131], v[182:185], v[108:111]
	v_mfma_f32_16x16x32_bf16 v[104:107], v[136:139], v[182:185], v[104:107]
	v_mfma_f32_16x16x32_bf16 v[92:95], v[128:131], v[218:221], v[92:95]
	v_mfma_f32_16x16x32_bf16 v[88:91], v[136:139], v[218:221], v[88:91]
	v_mfma_f32_16x16x32_bf16 v[76:79], v[128:131], v[226:229], v[76:79]
	v_mfma_f32_16x16x32_bf16 v[72:75], v[136:139], v[226:229], v[72:75]
	v_mfma_f32_16x16x32_bf16 v[120:123], v[132:135], v[178:181], v[120:123]
	v_mfma_f32_16x16x32_bf16 v[124:127], v[140:143], v[178:181], v[124:127]
	v_mfma_f32_16x16x32_bf16 v[108:111], v[132:135], v[186:189], v[108:111]
	v_mfma_f32_16x16x32_bf16 v[104:107], v[140:143], v[186:189], v[104:107]
	v_mfma_f32_16x16x32_bf16 v[92:95], v[132:135], v[222:225], v[92:95]
	v_mfma_f32_16x16x32_bf16 v[88:91], v[140:143], v[222:225], v[88:91]
	v_mfma_f32_16x16x32_bf16 v[76:79], v[132:135], v[230:233], v[76:79]
	v_mfma_f32_16x16x32_bf16 v[72:75], v[140:143], v[230:233], v[72:75]
	v_mfma_f32_16x16x32_bf16 v[116:119], v[154:157], v[174:177], v[116:119]
	v_mfma_f32_16x16x32_bf16 v[112:115], v[162:165], v[174:177], v[112:115]
	v_mfma_f32_16x16x32_bf16 v[100:103], v[154:157], v[182:185], v[100:103]
	v_mfma_f32_16x16x32_bf16 v[96:99], v[162:165], v[182:185], v[96:99]
	v_mfma_f32_16x16x32_bf16 v[84:87], v[154:157], v[218:221], v[84:87]
	v_mfma_f32_16x16x32_bf16 v[80:83], v[162:165], v[218:221], v[80:83]
	v_mfma_f32_16x16x32_bf16 v[68:71], v[154:157], v[226:229], v[68:71]
	v_mfma_f32_16x16x32_bf16 v[64:67], v[162:165], v[226:229], v[64:67]
	v_mfma_f32_16x16x32_bf16 v[116:119], v[158:161], v[178:181], v[116:119]
	v_mfma_f32_16x16x32_bf16 v[112:115], v[170:173], v[178:181], v[112:115]
	v_mfma_f32_16x16x32_bf16 v[100:103], v[158:161], v[186:189], v[100:103]
	v_mfma_f32_16x16x32_bf16 v[96:99], v[170:173], v[186:189], v[96:99]
	v_mfma_f32_16x16x32_bf16 v[84:87], v[158:161], v[222:225], v[84:87]
	v_mfma_f32_16x16x32_bf16 v[80:83], v[170:173], v[222:225], v[80:83]
	v_mfma_f32_16x16x32_bf16 v[68:71], v[158:161], v[230:233], v[68:71]
	v_mfma_f32_16x16x32_bf16 v[64:67], v[170:173], v[230:233], v[64:67]
	s_setprio 0
	s_barrier
	s_add_i32 s28, s73, s3
	v_lshl_add_u64 v[190:191], v[190:191], 0, s[38:39]
	s_mov_b32 m0, s28
	ds_read_b128 v[174:177], v169 offset:49152
	ds_read_b128 v[178:181], v169 offset:50176
	ds_read_b128 v[182:185], v169 offset:51200
	ds_read_b128 v[186:189], v169 offset:52224
	ds_read_b128 v[218:221], v169 offset:53248
	ds_read_b128 v[222:225], v169 offset:54272
	ds_read_b128 v[226:229], v169 offset:55296
	ds_read_b128 v[230:233], v169 offset:56320
	global_load_lds_dwordx4 v[190:191], off
	v_lshl_add_u64 v[190:191], v[198:199], 0, s[38:39]
	s_add_i32 m0, s28, 0x2000
	s_add_i32 s28, s82, s3
	global_load_lds_dwordx4 v[190:191], off
	v_lshl_add_u64 v[190:191], v[200:201], 0, s[38:39]
	s_mov_b32 m0, s28
	s_nop 0
	global_load_lds_dwordx4 v[190:191], off
	v_lshl_add_u64 v[190:191], v[234:235], 0, s[38:39]
	s_add_i32 m0, s28, 0x2000
	s_nop 0
	global_load_lds_dwordx4 v[190:191], off
	v_lshl_add_u64 v[190:191], v[236:237], 0, s[38:39]
	s_mov_b32 m0, s42
	s_nop 0
	global_load_lds_dwordx4 v[190:191], off
	v_lshl_add_u64 v[190:191], v[238:239], 0, s[38:39]
	s_mov_b32 m0, s43
	s_nop 0
	global_load_lds_dwordx4 v[190:191], off
	s_waitcnt vmcnt(8)
	s_waitcnt lgkmcnt(0)
	s_barrier
	s_setprio 1
	s_waitcnt lgkmcnt(0)
	v_mfma_f32_16x16x32_bf16 v[60:63], v[128:131], v[174:177], v[60:63]
	v_mfma_f32_16x16x32_bf16 v[56:59], v[136:139], v[174:177], v[56:59]
	v_mfma_f32_16x16x32_bf16 v[44:47], v[128:131], v[182:185], v[44:47]
	v_mfma_f32_16x16x32_bf16 v[40:43], v[136:139], v[182:185], v[40:43]
	v_mfma_f32_16x16x32_bf16 v[28:31], v[128:131], v[218:221], v[28:31]
	v_mfma_f32_16x16x32_bf16 v[24:27], v[136:139], v[218:221], v[24:27]
	v_mfma_f32_16x16x32_bf16 v[12:15], v[128:131], v[226:229], v[12:15]
	v_mfma_f32_16x16x32_bf16 v[8:11], v[136:139], v[226:229], v[8:11]
	v_mfma_f32_16x16x32_bf16 v[60:63], v[132:135], v[178:181], v[60:63]
	v_mfma_f32_16x16x32_bf16 v[56:59], v[140:143], v[178:181], v[56:59]
	v_mfma_f32_16x16x32_bf16 v[44:47], v[132:135], v[186:189], v[44:47]
	v_mfma_f32_16x16x32_bf16 v[40:43], v[140:143], v[186:189], v[40:43]
	v_mfma_f32_16x16x32_bf16 v[28:31], v[132:135], v[222:225], v[28:31]
	v_mfma_f32_16x16x32_bf16 v[24:27], v[140:143], v[222:225], v[24:27]
	v_mfma_f32_16x16x32_bf16 v[12:15], v[132:135], v[230:233], v[12:15]
	v_mfma_f32_16x16x32_bf16 v[8:11], v[140:143], v[230:233], v[8:11]
	v_mfma_f32_16x16x32_bf16 v[52:55], v[154:157], v[174:177], v[52:55]
	v_mfma_f32_16x16x32_bf16 v[48:51], v[162:165], v[174:177], v[48:51]
	v_mfma_f32_16x16x32_bf16 v[36:39], v[154:157], v[182:185], v[36:39]
	v_mfma_f32_16x16x32_bf16 v[32:35], v[162:165], v[182:185], v[32:35]
	v_mfma_f32_16x16x32_bf16 v[20:23], v[154:157], v[218:221], v[20:23]
	v_mfma_f32_16x16x32_bf16 v[16:19], v[162:165], v[218:221], v[16:19]
	v_mfma_f32_16x16x32_bf16 v[4:7], v[154:157], v[226:229], v[4:7]
	v_mfma_f32_16x16x32_bf16 v[0:3], v[162:165], v[226:229], v[0:3]
	v_mfma_f32_16x16x32_bf16 v[52:55], v[158:161], v[178:181], v[52:55]
	v_mfma_f32_16x16x32_bf16 v[48:51], v[170:173], v[178:181], v[48:51]
	v_mfma_f32_16x16x32_bf16 v[36:39], v[158:161], v[186:189], v[36:39]
	v_mfma_f32_16x16x32_bf16 v[32:35], v[170:173], v[186:189], v[32:35]
	v_mfma_f32_16x16x32_bf16 v[20:23], v[158:161], v[222:225], v[20:23]
	v_mfma_f32_16x16x32_bf16 v[16:19], v[170:173], v[222:225], v[16:19]
	v_mfma_f32_16x16x32_bf16 v[4:7], v[158:161], v[230:233], v[4:7]
	v_mfma_f32_16x16x32_bf16 v[0:3], v[170:173], v[230:233], v[0:3]
	s_setprio 0
	s_barrier
	s_add_u32 s24, s24, 0x100
	s_addc_u32 s25, s25, 0
	s_add_u32 s68, s68, 0x100
	s_addc_u32 s69, s69, 0
	s_cmp_ge_i32 s72, s26
	s_mov_b32 s28, s72
	s_cbranch_scc0 .LBB0_571
	s_movk_i32 s83, 0x7f

.LBB0_597:
	s_add_i32 s33, s26, 2
	s_add_u32 s28, s24, 0x80
	s_addc_u32 s29, s25, 0
	s_add_i32 s35, 0, 0x10000
	s_cmp_eq_u32 s92, s26
	s_cselect_b32 s29, s1, s29
	s_cselect_b32 s28, s0, s28
	s_cselect_b32 s43, s23, s20
	s_cselect_b32 s42, s22, s16
	s_add_i32 s26, 0, 0x14000
	v_add_u32_e32 v136, s35, v246
	v_add_u32_e32 v156, s26, v246
	ds_read_b128 v[112:115], v136
	ds_read_b128 v[120:123], v136 offset:1024
	ds_read_b128 v[128:131], v136 offset:2048
	ds_read_b128 v[136:139], v136 offset:3072
	ds_read_b128 v[140:143], v156
	ds_read_b128 v[148:151], v156 offset:1024
	ds_read_b128 v[152:155], v156 offset:2048
	ds_read_b128 v[156:159], v156 offset:3072
	v_lshl_add_u64 v[198:199], s[24:25], 0, v[224:225]
	s_add_i32 m0, s51, 0xc000
	ds_read_b128 v[160:163], v247
	ds_read_b128 v[164:167], v247 offset:1024
	ds_read_b128 v[168:171], v247 offset:2048
	ds_read_b128 v[172:175], v247 offset:3072
	ds_read_b128 v[176:179], v247 offset:4096
	ds_read_b128 v[180:183], v247 offset:5120
	ds_read_b128 v[184:187], v247 offset:6144
	ds_read_b128 v[188:191], v247 offset:7168
	global_load_lds_dwordx4 v[198:199], off
	v_lshl_add_u64 v[198:199], s[24:25], 0, v[226:227]
	s_add_i32 m0, s51, 0xe000
	s_nop 0
	global_load_lds_dwordx4 v[198:199], off
	s_waitcnt vmcnt(8)
	s_waitcnt lgkmcnt(0)
	s_barrier
	s_setprio 1
	s_waitcnt lgkmcnt(0)
	v_mfma_f32_16x16x32_bf16 v[144:147], v[112:115], v[160:163], v[144:147]
	v_mfma_f32_16x16x32_bf16 v[132:135], v[128:131], v[160:163], v[132:135]
	v_mfma_f32_16x16x32_bf16 v[108:111], v[112:115], v[168:171], v[108:111]
	v_mfma_f32_16x16x32_bf16 v[104:107], v[128:131], v[168:171], v[104:107]
	v_mfma_f32_16x16x32_bf16 v[92:95], v[112:115], v[176:179], v[92:95]
	v_mfma_f32_16x16x32_bf16 v[88:91], v[128:131], v[176:179], v[88:91]
	v_mfma_f32_16x16x32_bf16 v[76:79], v[112:115], v[184:187], v[76:79]
	v_mfma_f32_16x16x32_bf16 v[72:75], v[128:131], v[184:187], v[72:75]
	v_mfma_f32_16x16x32_bf16 v[144:147], v[120:123], v[164:167], v[144:147]
	v_mfma_f32_16x16x32_bf16 v[132:135], v[136:139], v[164:167], v[132:135]
	v_mfma_f32_16x16x32_bf16 v[108:111], v[120:123], v[172:175], v[108:111]
	v_mfma_f32_16x16x32_bf16 v[104:107], v[136:139], v[172:175], v[104:107]
	v_mfma_f32_16x16x32_bf16 v[92:95], v[120:123], v[180:183], v[92:95]
	v_mfma_f32_16x16x32_bf16 v[88:91], v[136:139], v[180:183], v[88:91]
	v_mfma_f32_16x16x32_bf16 v[76:79], v[120:123], v[188:191], v[76:79]
	v_mfma_f32_16x16x32_bf16 v[72:75], v[136:139], v[188:191], v[72:75]
	v_mfma_f32_16x16x32_bf16 v[124:127], v[140:143], v[160:163], v[124:127]
	v_mfma_f32_16x16x32_bf16 v[116:119], v[152:155], v[160:163], v[116:119]
	v_mfma_f32_16x16x32_bf16 v[100:103], v[140:143], v[168:171], v[100:103]
	v_mfma_f32_16x16x32_bf16 v[96:99], v[152:155], v[168:171], v[96:99]
	v_mfma_f32_16x16x32_bf16 v[84:87], v[140:143], v[176:179], v[84:87]
	v_mfma_f32_16x16x32_bf16 v[80:83], v[152:155], v[176:179], v[80:83]
	v_mfma_f32_16x16x32_bf16 v[68:71], v[140:143], v[184:187], v[68:71]
	v_mfma_f32_16x16x32_bf16 v[64:67], v[152:155], v[184:187], v[64:67]
	v_mfma_f32_16x16x32_bf16 v[124:127], v[148:151], v[164:167], v[124:127]
	v_mfma_f32_16x16x32_bf16 v[116:119], v[156:159], v[164:167], v[116:119]
	v_mfma_f32_16x16x32_bf16 v[100:103], v[148:151], v[172:175], v[100:103]
	v_mfma_f32_16x16x32_bf16 v[96:99], v[156:159], v[172:175], v[96:99]
	v_mfma_f32_16x16x32_bf16 v[84:87], v[148:151], v[180:183], v[84:87]
	v_mfma_f32_16x16x32_bf16 v[80:83], v[156:159], v[180:183], v[80:83]
	v_mfma_f32_16x16x32_bf16 v[68:71], v[148:151], v[188:191], v[68:71]
	v_mfma_f32_16x16x32_bf16 v[64:67], v[156:159], v[188:191], v[64:67]
	s_setprio 0
	s_barrier
	s_add_i32 s35, s35, s50
	v_lshl_add_u64 v[198:199], s[42:43], 0, v[194:195]
	s_mov_b32 m0, s35
	ds_read_b128 v[160:163], v247 offset:16384
	ds_read_b128 v[164:167], v247 offset:17408
	ds_read_b128 v[168:171], v247 offset:18432
	ds_read_b128 v[172:175], v247 offset:19456
	ds_read_b128 v[176:179], v247 offset:20480
	ds_read_b128 v[180:183], v247 offset:21504
	ds_read_b128 v[184:187], v247 offset:22528
	ds_read_b128 v[188:191], v247 offset:23552
	global_load_lds_dwordx4 v[198:199], off
	s_add_i32 m0, s35, 0x2000
	v_lshl_add_u64 v[200:201], s[42:43], 0, v[218:219]
	s_add_u32 s42, s42, s8
	s_addc_u32 s43, s43, s9
	s_add_i32 s26, s26, s50
	global_load_lds_dwordx4 v[200:201], off
	v_lshl_add_u64 v[228:229], s[42:43], 0, v[194:195]
	s_mov_b32 m0, s26
	v_lshl_add_u64 v[230:231], s[42:43], 0, v[218:219]
	global_load_lds_dwordx4 v[228:229], off
	s_add_i32 m0, s26, 0x2000
	v_lshl_add_u64 v[232:233], s[28:29], 0, v[222:223]
	global_load_lds_dwordx4 v[230:231], off
	s_mov_b32 m0, s51
	v_lshl_add_u64 v[234:235], s[28:29], 0, v[220:221]
	global_load_lds_dwordx4 v[232:233], off
	s_mov_b32 m0, s54
	s_nop 0
	global_load_lds_dwordx4 v[234:235], off
	s_waitcnt vmcnt(8)
	s_waitcnt lgkmcnt(0)
	s_barrier
	s_setprio 1
	s_waitcnt lgkmcnt(0)
	v_mfma_f32_16x16x32_bf16 v[60:63], v[112:115], v[160:163], v[60:63]
	v_mfma_f32_16x16x32_bf16 v[56:59], v[128:131], v[160:163], v[56:59]
	v_mfma_f32_16x16x32_bf16 v[44:47], v[112:115], v[168:171], v[44:47]
	v_mfma_f32_16x16x32_bf16 v[40:43], v[128:131], v[168:171], v[40:43]
	v_mfma_f32_16x16x32_bf16 v[28:31], v[112:115], v[176:179], v[28:31]
	v_mfma_f32_16x16x32_bf16 v[24:27], v[128:131], v[176:179], v[24:27]
	v_mfma_f32_16x16x32_bf16 v[12:15], v[112:115], v[184:187], v[12:15]
	v_mfma_f32_16x16x32_bf16 v[8:11], v[128:131], v[184:187], v[8:11]
	v_mfma_f32_16x16x32_bf16 v[60:63], v[120:123], v[164:167], v[60:63]
	v_mfma_f32_16x16x32_bf16 v[56:59], v[136:139], v[164:167], v[56:59]
	v_mfma_f32_16x16x32_bf16 v[44:47], v[120:123], v[172:175], v[44:47]
	v_mfma_f32_16x16x32_bf16 v[40:43], v[136:139], v[172:175], v[40:43]
	v_mfma_f32_16x16x32_bf16 v[28:31], v[120:123], v[180:183], v[28:31]
	v_mfma_f32_16x16x32_bf16 v[24:27], v[136:139], v[180:183], v[24:27]
	v_mfma_f32_16x16x32_bf16 v[12:15], v[120:123], v[188:191], v[12:15]
	v_mfma_f32_16x16x32_bf16 v[8:11], v[136:139], v[188:191], v[8:11]
	v_mfma_f32_16x16x32_bf16 v[52:55], v[140:143], v[160:163], v[52:55]
	v_mfma_f32_16x16x32_bf16 v[48:51], v[152:155], v[160:163], v[48:51]
	v_mfma_f32_16x16x32_bf16 v[36:39], v[140:143], v[168:171], v[36:39]
	v_mfma_f32_16x16x32_bf16 v[32:35], v[152:155], v[168:171], v[32:35]
	v_mfma_f32_16x16x32_bf16 v[20:23], v[140:143], v[176:179], v[20:23]
	v_mfma_f32_16x16x32_bf16 v[16:19], v[152:155], v[176:179], v[16:19]
	v_mfma_f32_16x16x32_bf16 v[4:7], v[140:143], v[184:187], v[4:7]
	v_mfma_f32_16x16x32_bf16 v[0:3], v[152:155], v[184:187], v[0:3]
	v_mfma_f32_16x16x32_bf16 v[52:55], v[148:151], v[164:167], v[52:55]
	v_mfma_f32_16x16x32_bf16 v[48:51], v[156:159], v[164:167], v[48:51]
	v_mfma_f32_16x16x32_bf16 v[36:39], v[148:151], v[172:175], v[36:39]
	v_mfma_f32_16x16x32_bf16 v[32:35], v[156:159], v[172:175], v[32:35]
	v_mfma_f32_16x16x32_bf16 v[20:23], v[148:151], v[180:183], v[20:23]
	v_mfma_f32_16x16x32_bf16 v[16:19], v[156:159], v[180:183], v[16:19]
	v_mfma_f32_16x16x32_bf16 v[4:7], v[148:151], v[188:191], v[4:7]
	v_mfma_f32_16x16x32_bf16 v[0:3], v[156:159], v[188:191], v[0:3]
	s_setprio 0
	s_barrier
	s_add_i32 s26, 0, 0x18000
	s_add_i32 s35, 0, 0x1c000
	v_add_u32_e32 v136, s26, v246
	v_add_u32_e32 v156, s35, v246
	ds_read_b128 v[112:115], v136
	ds_read_b128 v[120:123], v136 offset:1024
	ds_read_b128 v[128:131], v136 offset:2048
	ds_read_b128 v[136:139], v136 offset:3072
	ds_read_b128 v[140:143], v156
	ds_read_b128 v[148:151], v156 offset:1024
	ds_read_b128 v[152:155], v156 offset:2048
	ds_read_b128 v[156:159], v156 offset:3072
	s_add_u32 s28, s28, s8
	s_addc_u32 s29, s29, s9
	s_mov_b32 m0, s55
	v_lshl_add_u64 v[236:237], s[28:29], 0, v[222:223]
	ds_read_b128 v[160:163], v247 offset:32768
	ds_read_b128 v[164:167], v247 offset:33792
	ds_read_b128 v[168:171], v247 offset:34816
	ds_read_b128 v[172:175], v247 offset:35840
	ds_read_b128 v[176:179], v247 offset:36864
	ds_read_b128 v[180:183], v247 offset:37888
	ds_read_b128 v[184:187], v247 offset:38912
	ds_read_b128 v[188:191], v247 offset:39936
	global_load_lds_dwordx4 v[236:237], off
	v_lshl_add_u64 v[236:237], s[28:29], 0, v[220:221]
	s_mov_b32 m0, s68
	s_nop 0
	global_load_lds_dwordx4 v[236:237], off
	s_waitcnt vmcnt(8)
	s_waitcnt lgkmcnt(0)
	s_barrier
	s_setprio 1
	s_waitcnt lgkmcnt(0)
	v_mfma_f32_16x16x32_bf16 v[144:147], v[112:115], v[160:163], v[144:147]
	v_mfma_f32_16x16x32_bf16 v[132:135], v[128:131], v[160:163], v[132:135]
	v_mfma_f32_16x16x32_bf16 v[108:111], v[112:115], v[168:171], v[108:111]
	v_mfma_f32_16x16x32_bf16 v[104:107], v[128:131], v[168:171], v[104:107]
	v_mfma_f32_16x16x32_bf16 v[92:95], v[112:115], v[176:179], v[92:95]
	v_mfma_f32_16x16x32_bf16 v[88:91], v[128:131], v[176:179], v[88:91]
	v_mfma_f32_16x16x32_bf16 v[76:79], v[112:115], v[184:187], v[76:79]
	v_mfma_f32_16x16x32_bf16 v[72:75], v[128:131], v[184:187], v[72:75]
	v_mfma_f32_16x16x32_bf16 v[144:147], v[120:123], v[164:167], v[144:147]
	v_mfma_f32_16x16x32_bf16 v[132:135], v[136:139], v[164:167], v[132:135]
	v_mfma_f32_16x16x32_bf16 v[108:111], v[120:123], v[172:175], v[108:111]
	v_mfma_f32_16x16x32_bf16 v[104:107], v[136:139], v[172:175], v[104:107]
	v_mfma_f32_16x16x32_bf16 v[92:95], v[120:123], v[180:183], v[92:95]
	v_mfma_f32_16x16x32_bf16 v[88:91], v[136:139], v[180:183], v[88:91]
	v_mfma_f32_16x16x32_bf16 v[76:79], v[120:123], v[188:191], v[76:79]
	v_mfma_f32_16x16x32_bf16 v[72:75], v[136:139], v[188:191], v[72:75]
	v_mfma_f32_16x16x32_bf16 v[124:127], v[140:143], v[160:163], v[124:127]
	v_mfma_f32_16x16x32_bf16 v[116:119], v[152:155], v[160:163], v[116:119]
	v_mfma_f32_16x16x32_bf16 v[100:103], v[140:143], v[168:171], v[100:103]
	v_mfma_f32_16x16x32_bf16 v[96:99], v[152:155], v[168:171], v[96:99]
	v_mfma_f32_16x16x32_bf16 v[84:87], v[140:143], v[176:179], v[84:87]
	v_mfma_f32_16x16x32_bf16 v[80:83], v[152:155], v[176:179], v[80:83]
	v_mfma_f32_16x16x32_bf16 v[68:71], v[140:143], v[184:187], v[68:71]
	v_mfma_f32_16x16x32_bf16 v[64:67], v[152:155], v[184:187], v[64:67]
	v_mfma_f32_16x16x32_bf16 v[124:127], v[148:151], v[164:167], v[124:127]
	v_mfma_f32_16x16x32_bf16 v[116:119], v[156:159], v[164:167], v[116:119]
	v_mfma_f32_16x16x32_bf16 v[100:103], v[148:151], v[172:175], v[100:103]
	v_mfma_f32_16x16x32_bf16 v[96:99], v[156:159], v[172:175], v[96:99]
	v_mfma_f32_16x16x32_bf16 v[84:87], v[148:151], v[180:183], v[84:87]
	v_mfma_f32_16x16x32_bf16 v[80:83], v[156:159], v[180:183], v[80:83]
	v_mfma_f32_16x16x32_bf16 v[68:71], v[148:151], v[188:191], v[68:71]
	v_mfma_f32_16x16x32_bf16 v[64:67], v[156:159], v[188:191], v[64:67]
	s_setprio 0
	s_barrier
	s_add_i32 s26, s26, s50
	v_lshl_add_u64 v[198:199], v[198:199], 0, s[38:39]
	s_mov_b32 m0, s26
	ds_read_b128 v[160:163], v247 offset:49152
	ds_read_b128 v[164:167], v247 offset:50176
	ds_read_b128 v[168:171], v247 offset:51200
	ds_read_b128 v[172:175], v247 offset:52224
	ds_read_b128 v[176:179], v247 offset:53248
	ds_read_b128 v[180:183], v247 offset:54272
	ds_read_b128 v[184:187], v247 offset:55296
	ds_read_b128 v[188:191], v247 offset:56320
	global_load_lds_dwordx4 v[198:199], off
	v_lshl_add_u64 v[198:199], v[200:201], 0, s[38:39]
	s_add_i32 m0, s26, 0x2000
	s_add_i32 s26, s35, s50
	global_load_lds_dwordx4 v[198:199], off
	v_lshl_add_u64 v[198:199], v[228:229], 0, s[38:39]
	s_mov_b32 m0, s26
	s_nop 0
	global_load_lds_dwordx4 v[198:199], off
	v_lshl_add_u64 v[198:199], v[230:231], 0, s[38:39]
	s_add_i32 m0, s26, 0x2000
	s_nop 0
	global_load_lds_dwordx4 v[198:199], off
	v_lshl_add_u64 v[198:199], v[232:233], 0, s[38:39]
	s_mov_b32 m0, s88
	s_nop 0
	global_load_lds_dwordx4 v[198:199], off
	v_lshl_add_u64 v[198:199], v[234:235], 0, s[38:39]
	s_mov_b32 m0, s89
	s_nop 0
	global_load_lds_dwordx4 v[198:199], off
	s_waitcnt vmcnt(8)
	s_waitcnt lgkmcnt(0)
	s_barrier
	s_setprio 1
	s_waitcnt lgkmcnt(0)
	v_mfma_f32_16x16x32_bf16 v[60:63], v[112:115], v[160:163], v[60:63]
	v_mfma_f32_16x16x32_bf16 v[56:59], v[128:131], v[160:163], v[56:59]
	v_mfma_f32_16x16x32_bf16 v[44:47], v[112:115], v[168:171], v[44:47]
	v_mfma_f32_16x16x32_bf16 v[40:43], v[128:131], v[168:171], v[40:43]
	v_mfma_f32_16x16x32_bf16 v[28:31], v[112:115], v[176:179], v[28:31]
	v_mfma_f32_16x16x32_bf16 v[24:27], v[128:131], v[176:179], v[24:27]
	v_mfma_f32_16x16x32_bf16 v[12:15], v[112:115], v[184:187], v[12:15]
	v_mfma_f32_16x16x32_bf16 v[8:11], v[128:131], v[184:187], v[8:11]
	v_mfma_f32_16x16x32_bf16 v[60:63], v[120:123], v[164:167], v[60:63]
	v_mfma_f32_16x16x32_bf16 v[56:59], v[136:139], v[164:167], v[56:59]
	v_mfma_f32_16x16x32_bf16 v[44:47], v[120:123], v[172:175], v[44:47]
	v_mfma_f32_16x16x32_bf16 v[40:43], v[136:139], v[172:175], v[40:43]
	v_mfma_f32_16x16x32_bf16 v[28:31], v[120:123], v[180:183], v[28:31]
	v_mfma_f32_16x16x32_bf16 v[24:27], v[136:139], v[180:183], v[24:27]
	v_mfma_f32_16x16x32_bf16 v[12:15], v[120:123], v[188:191], v[12:15]
	v_mfma_f32_16x16x32_bf16 v[8:11], v[136:139], v[188:191], v[8:11]
	v_mfma_f32_16x16x32_bf16 v[52:55], v[140:143], v[160:163], v[52:55]
	v_mfma_f32_16x16x32_bf16 v[48:51], v[152:155], v[160:163], v[48:51]
	v_mfma_f32_16x16x32_bf16 v[36:39], v[140:143], v[168:171], v[36:39]
	v_mfma_f32_16x16x32_bf16 v[32:35], v[152:155], v[168:171], v[32:35]
	v_mfma_f32_16x16x32_bf16 v[20:23], v[140:143], v[176:179], v[20:23]
	v_mfma_f32_16x16x32_bf16 v[16:19], v[152:155], v[176:179], v[16:19]
	v_mfma_f32_16x16x32_bf16 v[4:7], v[140:143], v[184:187], v[4:7]
	v_mfma_f32_16x16x32_bf16 v[0:3], v[152:155], v[184:187], v[0:3]
	v_mfma_f32_16x16x32_bf16 v[52:55], v[148:151], v[164:167], v[52:55]
	v_mfma_f32_16x16x32_bf16 v[48:51], v[156:159], v[164:167], v[48:51]
	v_mfma_f32_16x16x32_bf16 v[36:39], v[148:151], v[172:175], v[36:39]
	v_mfma_f32_16x16x32_bf16 v[32:35], v[156:159], v[172:175], v[32:35]
	v_mfma_f32_16x16x32_bf16 v[20:23], v[148:151], v[180:183], v[20:23]
	v_mfma_f32_16x16x32_bf16 v[16:19], v[156:159], v[180:183], v[16:19]
	v_mfma_f32_16x16x32_bf16 v[4:7], v[148:151], v[188:191], v[4:7]
	v_mfma_f32_16x16x32_bf16 v[0:3], v[156:159], v[188:191], v[0:3]
	s_setprio 0
	s_barrier
	s_add_u32 s24, s24, 0x100
	s_addc_u32 s25, s25, 0
	s_add_u32 s16, s16, 0x100
	s_addc_u32 s20, s20, 0
	s_cmp_ge_i32 s33, s69
	s_mov_b32 s26, s33
	s_cbranch_scc0 .LBB0_597

.LBB0_680:
	s_add_i32 s83, s28, 2
	s_add_u32 s86, s24, 0x80
	s_addc_u32 s29, s25, 0
	s_add_i32 s88, 0, 0x10000
	s_cmp_eq_u32 s49, s28
	s_cselect_b32 s29, s1, s29
	s_cselect_b32 s28, s0, s86
	s_cselect_b32 s87, s69, s82
	s_cselect_b32 s86, s68, s73
	s_add_i32 s89, 0, 0x14000
	v_add_u32_e32 v140, s88, v186
	v_add_u32_e32 v166, s89, v186
	ds_read_b128 v[128:131], v140
	ds_read_b128 v[132:135], v140 offset:1024
	ds_read_b128 v[136:139], v140 offset:2048
	ds_read_b128 v[140:143], v140 offset:3072
	ds_read_b128 v[144:147], v166
	ds_read_b128 v[148:151], v166 offset:1024
	ds_read_b128 v[152:155], v166 offset:2048
	ds_read_b128 v[166:169], v166 offset:3072
	v_lshl_add_u64 v[182:183], s[24:25], 0, v[162:163]
	s_add_i32 m0, s16, 0xc000
	ds_read_b128 v[170:173], v187
	ds_read_b128 v[174:177], v187 offset:1024
	ds_read_b128 v[178:181], v187 offset:2048
	ds_read_b128 v[188:191], v187 offset:3072
	ds_read_b128 v[198:201], v187 offset:4096
	ds_read_b128 v[218:221], v187 offset:5120
	ds_read_b128 v[222:225], v187 offset:6144
	ds_read_b128 v[226:229], v187 offset:7168
	global_load_lds_dwordx4 v[182:183], off
	v_lshl_add_u64 v[182:183], s[24:25], 0, v[164:165]
	s_add_i32 m0, s16, 0xe000
	s_nop 0
	global_load_lds_dwordx4 v[182:183], off
	s_waitcnt vmcnt(8)
	s_waitcnt lgkmcnt(0)
	s_barrier
	s_setprio 1
	s_waitcnt lgkmcnt(0)
	v_mfma_f32_16x16x32_bf16 v[120:123], v[128:131], v[170:173], v[120:123]
	v_mfma_f32_16x16x32_bf16 v[124:127], v[136:139], v[170:173], v[124:127]
	v_mfma_f32_16x16x32_bf16 v[108:111], v[128:131], v[178:181], v[108:111]
	v_mfma_f32_16x16x32_bf16 v[104:107], v[136:139], v[178:181], v[104:107]
	v_mfma_f32_16x16x32_bf16 v[92:95], v[128:131], v[198:201], v[92:95]
	v_mfma_f32_16x16x32_bf16 v[88:91], v[136:139], v[198:201], v[88:91]
	v_mfma_f32_16x16x32_bf16 v[76:79], v[128:131], v[222:225], v[76:79]
	v_mfma_f32_16x16x32_bf16 v[72:75], v[136:139], v[222:225], v[72:75]
	v_mfma_f32_16x16x32_bf16 v[120:123], v[132:135], v[174:177], v[120:123]
	v_mfma_f32_16x16x32_bf16 v[124:127], v[140:143], v[174:177], v[124:127]
	v_mfma_f32_16x16x32_bf16 v[108:111], v[132:135], v[188:191], v[108:111]
	v_mfma_f32_16x16x32_bf16 v[104:107], v[140:143], v[188:191], v[104:107]
	v_mfma_f32_16x16x32_bf16 v[92:95], v[132:135], v[218:221], v[92:95]
	v_mfma_f32_16x16x32_bf16 v[88:91], v[140:143], v[218:221], v[88:91]
	v_mfma_f32_16x16x32_bf16 v[76:79], v[132:135], v[226:229], v[76:79]
	v_mfma_f32_16x16x32_bf16 v[72:75], v[140:143], v[226:229], v[72:75]
	v_mfma_f32_16x16x32_bf16 v[116:119], v[144:147], v[170:173], v[116:119]
	v_mfma_f32_16x16x32_bf16 v[112:115], v[152:155], v[170:173], v[112:115]
	v_mfma_f32_16x16x32_bf16 v[100:103], v[144:147], v[178:181], v[100:103]
	v_mfma_f32_16x16x32_bf16 v[96:99], v[152:155], v[178:181], v[96:99]
	v_mfma_f32_16x16x32_bf16 v[84:87], v[144:147], v[198:201], v[84:87]
	v_mfma_f32_16x16x32_bf16 v[80:83], v[152:155], v[198:201], v[80:83]
	v_mfma_f32_16x16x32_bf16 v[68:71], v[144:147], v[222:225], v[68:71]
	v_mfma_f32_16x16x32_bf16 v[64:67], v[152:155], v[222:225], v[64:67]
	v_mfma_f32_16x16x32_bf16 v[116:119], v[148:151], v[174:177], v[116:119]
	v_mfma_f32_16x16x32_bf16 v[112:115], v[166:169], v[174:177], v[112:115]
	v_mfma_f32_16x16x32_bf16 v[100:103], v[148:151], v[188:191], v[100:103]
	v_mfma_f32_16x16x32_bf16 v[96:99], v[166:169], v[188:191], v[96:99]
	v_mfma_f32_16x16x32_bf16 v[84:87], v[148:151], v[218:221], v[84:87]
	v_mfma_f32_16x16x32_bf16 v[80:83], v[166:169], v[218:221], v[80:83]
	v_mfma_f32_16x16x32_bf16 v[68:71], v[148:151], v[226:229], v[68:71]
	v_mfma_f32_16x16x32_bf16 v[64:67], v[166:169], v[226:229], v[64:67]
	s_setprio 0
	s_barrier
	s_add_i32 s88, s88, s7
	v_lshl_add_u64 v[182:183], s[86:87], 0, v[194:195]
	s_mov_b32 m0, s88
	ds_read_b128 v[170:173], v187 offset:16384
	ds_read_b128 v[174:177], v187 offset:17408
	ds_read_b128 v[178:181], v187 offset:18432
	ds_read_b128 v[188:191], v187 offset:19456
	ds_read_b128 v[198:201], v187 offset:20480
	ds_read_b128 v[218:221], v187 offset:21504
	ds_read_b128 v[222:225], v187 offset:22528
	ds_read_b128 v[226:229], v187 offset:23552
	global_load_lds_dwordx4 v[182:183], off
	s_add_i32 m0, s88, 0x2000
	v_lshl_add_u64 v[230:231], s[86:87], 0, v[156:157]
	s_add_u32 s86, s86, s8
	s_addc_u32 s87, s87, s9
	s_add_i32 s88, s89, s7
	global_load_lds_dwordx4 v[230:231], off
	v_lshl_add_u64 v[232:233], s[86:87], 0, v[194:195]
	s_mov_b32 m0, s88
	v_lshl_add_u64 v[234:235], s[86:87], 0, v[156:157]
	global_load_lds_dwordx4 v[232:233], off
	s_add_i32 m0, s88, 0x2000
	v_lshl_add_u64 v[236:237], s[28:29], 0, v[160:161]
	global_load_lds_dwordx4 v[234:235], off
	s_mov_b32 m0, s16
	v_lshl_add_u64 v[238:239], s[28:29], 0, v[158:159]
	global_load_lds_dwordx4 v[236:237], off
	s_mov_b32 m0, s20
	s_nop 0
	global_load_lds_dwordx4 v[238:239], off
	s_waitcnt vmcnt(8)
	s_waitcnt lgkmcnt(0)
	s_barrier
	s_setprio 1
	s_waitcnt lgkmcnt(0)
	v_mfma_f32_16x16x32_bf16 v[60:63], v[128:131], v[170:173], v[60:63]
	v_mfma_f32_16x16x32_bf16 v[56:59], v[136:139], v[170:173], v[56:59]
	v_mfma_f32_16x16x32_bf16 v[44:47], v[128:131], v[178:181], v[44:47]
	v_mfma_f32_16x16x32_bf16 v[40:43], v[136:139], v[178:181], v[40:43]
	v_mfma_f32_16x16x32_bf16 v[28:31], v[128:131], v[198:201], v[28:31]
	v_mfma_f32_16x16x32_bf16 v[24:27], v[136:139], v[198:201], v[24:27]
	v_mfma_f32_16x16x32_bf16 v[12:15], v[128:131], v[222:225], v[12:15]
	v_mfma_f32_16x16x32_bf16 v[8:11], v[136:139], v[222:225], v[8:11]
	v_mfma_f32_16x16x32_bf16 v[60:63], v[132:135], v[174:177], v[60:63]
	v_mfma_f32_16x16x32_bf16 v[56:59], v[140:143], v[174:177], v[56:59]
	v_mfma_f32_16x16x32_bf16 v[44:47], v[132:135], v[188:191], v[44:47]
	v_mfma_f32_16x16x32_bf16 v[40:43], v[140:143], v[188:191], v[40:43]
	v_mfma_f32_16x16x32_bf16 v[28:31], v[132:135], v[218:221], v[28:31]
	v_mfma_f32_16x16x32_bf16 v[24:27], v[140:143], v[218:221], v[24:27]
	v_mfma_f32_16x16x32_bf16 v[12:15], v[132:135], v[226:229], v[12:15]
	v_mfma_f32_16x16x32_bf16 v[8:11], v[140:143], v[226:229], v[8:11]
	v_mfma_f32_16x16x32_bf16 v[52:55], v[144:147], v[170:173], v[52:55]
	v_mfma_f32_16x16x32_bf16 v[48:51], v[152:155], v[170:173], v[48:51]
	v_mfma_f32_16x16x32_bf16 v[36:39], v[144:147], v[178:181], v[36:39]
	v_mfma_f32_16x16x32_bf16 v[32:35], v[152:155], v[178:181], v[32:35]
	v_mfma_f32_16x16x32_bf16 v[20:23], v[144:147], v[198:201], v[20:23]
	v_mfma_f32_16x16x32_bf16 v[16:19], v[152:155], v[198:201], v[16:19]
	v_mfma_f32_16x16x32_bf16 v[4:7], v[144:147], v[222:225], v[4:7]
	v_mfma_f32_16x16x32_bf16 v[0:3], v[152:155], v[222:225], v[0:3]
	v_mfma_f32_16x16x32_bf16 v[52:55], v[148:151], v[174:177], v[52:55]
	v_mfma_f32_16x16x32_bf16 v[48:51], v[166:169], v[174:177], v[48:51]
	v_mfma_f32_16x16x32_bf16 v[36:39], v[148:151], v[188:191], v[36:39]
	v_mfma_f32_16x16x32_bf16 v[32:35], v[166:169], v[188:191], v[32:35]
	v_mfma_f32_16x16x32_bf16 v[20:23], v[148:151], v[218:221], v[20:23]
	v_mfma_f32_16x16x32_bf16 v[16:19], v[166:169], v[218:221], v[16:19]
	v_mfma_f32_16x16x32_bf16 v[4:7], v[148:151], v[226:229], v[4:7]
	v_mfma_f32_16x16x32_bf16 v[0:3], v[166:169], v[226:229], v[0:3]
	s_setprio 0
	s_barrier
	s_add_i32 s86, 0, 0x18000
	s_add_i32 s87, 0, 0x1c000
	v_add_u32_e32 v140, s86, v186
	v_add_u32_e32 v166, s87, v186
	ds_read_b128 v[128:131], v140
	ds_read_b128 v[132:135], v140 offset:1024
	ds_read_b128 v[136:139], v140 offset:2048
	ds_read_b128 v[140:143], v140 offset:3072
	ds_read_b128 v[144:147], v166
	ds_read_b128 v[148:151], v166 offset:1024
	ds_read_b128 v[152:155], v166 offset:2048
	ds_read_b128 v[166:169], v166 offset:3072
	s_add_u32 s28, s28, s8
	s_addc_u32 s29, s29, s9
	s_mov_b32 m0, s26
	v_lshl_add_u64 v[240:241], s[28:29], 0, v[160:161]
	ds_read_b128 v[170:173], v187 offset:32768
	ds_read_b128 v[174:177], v187 offset:33792
	ds_read_b128 v[178:181], v187 offset:34816
	ds_read_b128 v[188:191], v187 offset:35840
	ds_read_b128 v[198:201], v187 offset:36864
	ds_read_b128 v[218:221], v187 offset:37888
	ds_read_b128 v[222:225], v187 offset:38912
	ds_read_b128 v[226:229], v187 offset:39936
	global_load_lds_dwordx4 v[240:241], off
	v_lshl_add_u64 v[240:241], s[28:29], 0, v[158:159]
	s_mov_b32 m0, s30
	s_nop 0
	global_load_lds_dwordx4 v[240:241], off
	s_waitcnt vmcnt(8)
	s_waitcnt lgkmcnt(0)
	s_barrier
	s_setprio 1
	s_waitcnt lgkmcnt(0)
	v_mfma_f32_16x16x32_bf16 v[120:123], v[128:131], v[170:173], v[120:123]
	v_mfma_f32_16x16x32_bf16 v[124:127], v[136:139], v[170:173], v[124:127]
	v_mfma_f32_16x16x32_bf16 v[108:111], v[128:131], v[178:181], v[108:111]
	v_mfma_f32_16x16x32_bf16 v[104:107], v[136:139], v[178:181], v[104:107]
	v_mfma_f32_16x16x32_bf16 v[92:95], v[128:131], v[198:201], v[92:95]
	v_mfma_f32_16x16x32_bf16 v[88:91], v[136:139], v[198:201], v[88:91]
	v_mfma_f32_16x16x32_bf16 v[76:79], v[128:131], v[222:225], v[76:79]
	v_mfma_f32_16x16x32_bf16 v[72:75], v[136:139], v[222:225], v[72:75]
	v_mfma_f32_16x16x32_bf16 v[120:123], v[132:135], v[174:177], v[120:123]
	v_mfma_f32_16x16x32_bf16 v[124:127], v[140:143], v[174:177], v[124:127]
	v_mfma_f32_16x16x32_bf16 v[108:111], v[132:135], v[188:191], v[108:111]
	v_mfma_f32_16x16x32_bf16 v[104:107], v[140:143], v[188:191], v[104:107]
	v_mfma_f32_16x16x32_bf16 v[92:95], v[132:135], v[218:221], v[92:95]
	v_mfma_f32_16x16x32_bf16 v[88:91], v[140:143], v[218:221], v[88:91]
	v_mfma_f32_16x16x32_bf16 v[76:79], v[132:135], v[226:229], v[76:79]
	v_mfma_f32_16x16x32_bf16 v[72:75], v[140:143], v[226:229], v[72:75]
	v_mfma_f32_16x16x32_bf16 v[116:119], v[144:147], v[170:173], v[116:119]
	v_mfma_f32_16x16x32_bf16 v[112:115], v[152:155], v[170:173], v[112:115]
	v_mfma_f32_16x16x32_bf16 v[100:103], v[144:147], v[178:181], v[100:103]
	v_mfma_f32_16x16x32_bf16 v[96:99], v[152:155], v[178:181], v[96:99]
	v_mfma_f32_16x16x32_bf16 v[84:87], v[144:147], v[198:201], v[84:87]
	v_mfma_f32_16x16x32_bf16 v[80:83], v[152:155], v[198:201], v[80:83]
	v_mfma_f32_16x16x32_bf16 v[68:71], v[144:147], v[222:225], v[68:71]
	v_mfma_f32_16x16x32_bf16 v[64:67], v[152:155], v[222:225], v[64:67]
	v_mfma_f32_16x16x32_bf16 v[116:119], v[148:151], v[174:177], v[116:119]
	v_mfma_f32_16x16x32_bf16 v[112:115], v[166:169], v[174:177], v[112:115]
	v_mfma_f32_16x16x32_bf16 v[100:103], v[148:151], v[188:191], v[100:103]
	v_mfma_f32_16x16x32_bf16 v[96:99], v[166:169], v[188:191], v[96:99]
	v_mfma_f32_16x16x32_bf16 v[84:87], v[148:151], v[218:221], v[84:87]
	v_mfma_f32_16x16x32_bf16 v[80:83], v[166:169], v[218:221], v[80:83]
	v_mfma_f32_16x16x32_bf16 v[68:71], v[148:151], v[226:229], v[68:71]
	v_mfma_f32_16x16x32_bf16 v[64:67], v[166:169], v[226:229], v[64:67]
	s_setprio 0
	s_barrier
	s_add_i32 s28, s86, s7
	v_lshl_add_u64 v[182:183], v[182:183], 0, s[38:39]
	s_mov_b32 m0, s28
	ds_read_b128 v[170:173], v187 offset:49152
	ds_read_b128 v[174:177], v187 offset:50176
	ds_read_b128 v[178:181], v187 offset:51200
	ds_read_b128 v[188:191], v187 offset:52224
	ds_read_b128 v[198:201], v187 offset:53248
	ds_read_b128 v[218:221], v187 offset:54272
	ds_read_b128 v[222:225], v187 offset:55296
	ds_read_b128 v[226:229], v187 offset:56320
	global_load_lds_dwordx4 v[182:183], off
	v_lshl_add_u64 v[182:183], v[230:231], 0, s[38:39]
	s_add_i32 m0, s28, 0x2000
	s_add_i32 s28, s87, s7
	global_load_lds_dwordx4 v[182:183], off
	v_lshl_add_u64 v[182:183], v[232:233], 0, s[38:39]
	s_mov_b32 m0, s28
	s_nop 0
	global_load_lds_dwordx4 v[182:183], off
	v_lshl_add_u64 v[182:183], v[234:235], 0, s[38:39]
	s_add_i32 m0, s28, 0x2000
	s_nop 0
	global_load_lds_dwordx4 v[182:183], off
	v_lshl_add_u64 v[182:183], v[236:237], 0, s[38:39]
	s_mov_b32 m0, s43
	s_nop 0
	global_load_lds_dwordx4 v[182:183], off
	v_lshl_add_u64 v[182:183], v[238:239], 0, s[38:39]
	s_mov_b32 m0, s48
	s_nop 0
	global_load_lds_dwordx4 v[182:183], off
	s_waitcnt vmcnt(8)
	s_waitcnt lgkmcnt(0)
	s_barrier
	s_setprio 1
	s_waitcnt lgkmcnt(0)
	v_mfma_f32_16x16x32_bf16 v[60:63], v[128:131], v[170:173], v[60:63]
	v_mfma_f32_16x16x32_bf16 v[56:59], v[136:139], v[170:173], v[56:59]
	v_mfma_f32_16x16x32_bf16 v[44:47], v[128:131], v[178:181], v[44:47]
	v_mfma_f32_16x16x32_bf16 v[40:43], v[136:139], v[178:181], v[40:43]
	v_mfma_f32_16x16x32_bf16 v[28:31], v[128:131], v[198:201], v[28:31]
	v_mfma_f32_16x16x32_bf16 v[24:27], v[136:139], v[198:201], v[24:27]
	v_mfma_f32_16x16x32_bf16 v[12:15], v[128:131], v[222:225], v[12:15]
	v_mfma_f32_16x16x32_bf16 v[8:11], v[136:139], v[222:225], v[8:11]
	v_mfma_f32_16x16x32_bf16 v[60:63], v[132:135], v[174:177], v[60:63]
	v_mfma_f32_16x16x32_bf16 v[56:59], v[140:143], v[174:177], v[56:59]
	v_mfma_f32_16x16x32_bf16 v[44:47], v[132:135], v[188:191], v[44:47]
	v_mfma_f32_16x16x32_bf16 v[40:43], v[140:143], v[188:191], v[40:43]
	v_mfma_f32_16x16x32_bf16 v[28:31], v[132:135], v[218:221], v[28:31]
	v_mfma_f32_16x16x32_bf16 v[24:27], v[140:143], v[218:221], v[24:27]
	v_mfma_f32_16x16x32_bf16 v[12:15], v[132:135], v[226:229], v[12:15]
	v_mfma_f32_16x16x32_bf16 v[8:11], v[140:143], v[226:229], v[8:11]
	v_mfma_f32_16x16x32_bf16 v[52:55], v[144:147], v[170:173], v[52:55]
	v_mfma_f32_16x16x32_bf16 v[48:51], v[152:155], v[170:173], v[48:51]
	v_mfma_f32_16x16x32_bf16 v[36:39], v[144:147], v[178:181], v[36:39]
	v_mfma_f32_16x16x32_bf16 v[32:35], v[152:155], v[178:181], v[32:35]
	v_mfma_f32_16x16x32_bf16 v[20:23], v[144:147], v[198:201], v[20:23]
	v_mfma_f32_16x16x32_bf16 v[16:19], v[152:155], v[198:201], v[16:19]
	v_mfma_f32_16x16x32_bf16 v[4:7], v[144:147], v[222:225], v[4:7]
	v_mfma_f32_16x16x32_bf16 v[0:3], v[152:155], v[222:225], v[0:3]
	v_mfma_f32_16x16x32_bf16 v[52:55], v[148:151], v[174:177], v[52:55]
	v_mfma_f32_16x16x32_bf16 v[48:51], v[166:169], v[174:177], v[48:51]
	v_mfma_f32_16x16x32_bf16 v[36:39], v[148:151], v[188:191], v[36:39]
	v_mfma_f32_16x16x32_bf16 v[32:35], v[166:169], v[188:191], v[32:35]
	v_mfma_f32_16x16x32_bf16 v[20:23], v[148:151], v[218:221], v[20:23]
	v_mfma_f32_16x16x32_bf16 v[16:19], v[166:169], v[218:221], v[16:19]
	v_mfma_f32_16x16x32_bf16 v[4:7], v[148:151], v[226:229], v[4:7]
	v_mfma_f32_16x16x32_bf16 v[0:3], v[166:169], v[226:229], v[0:3]
	s_setprio 0
	s_barrier
	s_add_u32 s24, s24, 0x100
	s_addc_u32 s25, s25, 0
	s_add_u32 s73, s73, 0x100
	s_addc_u32 s82, s82, 0
	s_cmp_ge_i32 s83, s33
	s_mov_b32 s28, s83
	s_cbranch_scc0 .LBB0_680
	s_movk_i32 s83, 0x7f

.LBB0_782:
	s_add_i32 s72, s24, 2
	s_add_u32 s73, s4, 0x80
	s_addc_u32 s25, s5, 0
	s_add_i32 s88, 0, 0x10000
	s_cmp_eq_u32 s48, s24
	s_cselect_b32 s25, s69, s25
	s_cselect_b32 s24, s68, s73
	v_add_u32_e32 v146, s88, v155
	s_cselect_b32 s83, s87, s29
	s_cselect_b32 s82, s86, s28
	s_add_i32 s73, 0, 0x14000
	ds_read_b128 v[128:131], v146
	ds_read_b128 v[142:145], v146 offset:1024
	ds_read_b128 v[150:153], v146 offset:2048
	ds_read_b128 v[160:163], v146 offset:3072
	v_add_u32_e32 v146, s73, v155
	ds_read_b128 v[164:167], v146
	ds_read_b128 v[168:171], v146 offset:1024
	ds_read_b128 v[172:175], v146 offset:2048
	ds_read_b128 v[176:179], v146 offset:3072
	v_lshl_add_u64 v[156:157], s[4:5], 0, v[138:139]
	s_add_i32 m0, s16, 0xc000
	ds_read_b128 v[180:183], v159
	ds_read_b128 v[184:187], v159 offset:1024
	ds_read_b128 v[188:191], v159 offset:2048
	ds_read_b128 v[198:201], v159 offset:3072
	ds_read_b128 v[218:221], v159 offset:4096
	ds_read_b128 v[222:225], v159 offset:5120
	ds_read_b128 v[226:229], v159 offset:6144
	ds_read_b128 v[230:233], v159 offset:7168
	global_load_lds_dwordx4 v[156:157], off
	v_lshl_add_u64 v[156:157], s[4:5], 0, v[140:141]
	s_add_i32 m0, s16, 0xe000
	s_nop 0
	global_load_lds_dwordx4 v[156:157], off
	s_waitcnt vmcnt(8)
	s_waitcnt lgkmcnt(0)
	s_barrier
	s_setprio 1
	s_waitcnt lgkmcnt(0)
	v_mfma_f32_16x16x32_bf16 v[124:127], v[128:131], v[180:183], v[124:127]
	v_mfma_f32_16x16x32_bf16 v[120:123], v[150:153], v[180:183], v[120:123]
	v_mfma_f32_16x16x32_bf16 v[108:111], v[128:131], v[188:191], v[108:111]
	v_mfma_f32_16x16x32_bf16 v[104:107], v[150:153], v[188:191], v[104:107]
	v_mfma_f32_16x16x32_bf16 v[92:95], v[128:131], v[218:221], v[92:95]
	v_mfma_f32_16x16x32_bf16 v[88:91], v[150:153], v[218:221], v[88:91]
	v_mfma_f32_16x16x32_bf16 v[76:79], v[128:131], v[226:229], v[76:79]
	v_mfma_f32_16x16x32_bf16 v[72:75], v[150:153], v[226:229], v[72:75]
	v_mfma_f32_16x16x32_bf16 v[124:127], v[142:145], v[184:187], v[124:127]
	v_mfma_f32_16x16x32_bf16 v[120:123], v[160:163], v[184:187], v[120:123]
	v_mfma_f32_16x16x32_bf16 v[108:111], v[142:145], v[198:201], v[108:111]
	v_mfma_f32_16x16x32_bf16 v[104:107], v[160:163], v[198:201], v[104:107]
	v_mfma_f32_16x16x32_bf16 v[92:95], v[142:145], v[222:225], v[92:95]
	v_mfma_f32_16x16x32_bf16 v[88:91], v[160:163], v[222:225], v[88:91]
	v_mfma_f32_16x16x32_bf16 v[76:79], v[142:145], v[230:233], v[76:79]
	v_mfma_f32_16x16x32_bf16 v[72:75], v[160:163], v[230:233], v[72:75]
	v_mfma_f32_16x16x32_bf16 v[116:119], v[164:167], v[180:183], v[116:119]
	v_mfma_f32_16x16x32_bf16 v[112:115], v[172:175], v[180:183], v[112:115]
	v_mfma_f32_16x16x32_bf16 v[100:103], v[164:167], v[188:191], v[100:103]
	v_mfma_f32_16x16x32_bf16 v[96:99], v[172:175], v[188:191], v[96:99]
	v_mfma_f32_16x16x32_bf16 v[84:87], v[164:167], v[218:221], v[84:87]
	v_mfma_f32_16x16x32_bf16 v[80:83], v[172:175], v[218:221], v[80:83]
	v_mfma_f32_16x16x32_bf16 v[68:71], v[164:167], v[226:229], v[68:71]
	v_mfma_f32_16x16x32_bf16 v[64:67], v[172:175], v[226:229], v[64:67]
	v_mfma_f32_16x16x32_bf16 v[116:119], v[168:171], v[184:187], v[116:119]
	v_mfma_f32_16x16x32_bf16 v[112:115], v[176:179], v[184:187], v[112:115]
	v_mfma_f32_16x16x32_bf16 v[100:103], v[168:171], v[198:201], v[100:103]
	v_mfma_f32_16x16x32_bf16 v[96:99], v[176:179], v[198:201], v[96:99]
	v_mfma_f32_16x16x32_bf16 v[84:87], v[168:171], v[222:225], v[84:87]
	v_mfma_f32_16x16x32_bf16 v[80:83], v[176:179], v[222:225], v[80:83]
	v_mfma_f32_16x16x32_bf16 v[68:71], v[168:171], v[230:233], v[68:71]
	v_mfma_f32_16x16x32_bf16 v[64:67], v[176:179], v[230:233], v[64:67]
	s_setprio 0
	s_barrier
	s_add_i32 s88, s88, s7
	v_lshl_add_u64 v[156:157], s[82:83], 0, v[194:195]
	s_mov_b32 m0, s88
	ds_read_b128 v[180:183], v159 offset:16384
	ds_read_b128 v[184:187], v159 offset:17408
	ds_read_b128 v[188:191], v159 offset:18432
	ds_read_b128 v[198:201], v159 offset:19456
	ds_read_b128 v[218:221], v159 offset:20480
	ds_read_b128 v[222:225], v159 offset:21504
	ds_read_b128 v[226:229], v159 offset:22528
	ds_read_b128 v[230:233], v159 offset:23552
	global_load_lds_dwordx4 v[156:157], off
	s_add_i32 m0, s88, 0x2000
	v_lshl_add_u64 v[234:235], s[82:83], 0, v[132:133]
	s_add_u32 s82, s82, s8
	s_addc_u32 s83, s83, s9
	s_add_i32 s73, s73, s7
	global_load_lds_dwordx4 v[234:235], off
	v_lshl_add_u64 v[236:237], s[82:83], 0, v[194:195]
	s_mov_b32 m0, s73
	v_lshl_add_u64 v[238:239], s[82:83], 0, v[132:133]
	global_load_lds_dwordx4 v[236:237], off
	s_add_i32 m0, s73, 0x2000
	v_lshl_add_u64 v[240:241], s[24:25], 0, v[136:137]
	global_load_lds_dwordx4 v[238:239], off
	s_mov_b32 m0, s16
	v_lshl_add_u64 v[246:247], s[24:25], 0, v[134:135]
	global_load_lds_dwordx4 v[240:241], off
	s_mov_b32 m0, s20
	s_nop 0
	global_load_lds_dwordx4 v[246:247], off
	s_waitcnt vmcnt(8)
	s_waitcnt lgkmcnt(0)
	s_barrier
	s_setprio 1
	s_waitcnt lgkmcnt(0)
	v_mfma_f32_16x16x32_bf16 v[60:63], v[128:131], v[180:183], v[60:63]
	v_mfma_f32_16x16x32_bf16 v[56:59], v[150:153], v[180:183], v[56:59]
	v_mfma_f32_16x16x32_bf16 v[44:47], v[128:131], v[188:191], v[44:47]
	v_mfma_f32_16x16x32_bf16 v[40:43], v[150:153], v[188:191], v[40:43]
	v_mfma_f32_16x16x32_bf16 v[28:31], v[128:131], v[218:221], v[28:31]
	v_mfma_f32_16x16x32_bf16 v[24:27], v[150:153], v[218:221], v[24:27]
	v_mfma_f32_16x16x32_bf16 v[12:15], v[128:131], v[226:229], v[12:15]
	v_mfma_f32_16x16x32_bf16 v[8:11], v[150:153], v[226:229], v[8:11]
	v_mfma_f32_16x16x32_bf16 v[60:63], v[142:145], v[184:187], v[60:63]
	v_mfma_f32_16x16x32_bf16 v[56:59], v[160:163], v[184:187], v[56:59]
	v_mfma_f32_16x16x32_bf16 v[44:47], v[142:145], v[198:201], v[44:47]
	v_mfma_f32_16x16x32_bf16 v[40:43], v[160:163], v[198:201], v[40:43]
	v_mfma_f32_16x16x32_bf16 v[28:31], v[142:145], v[222:225], v[28:31]
	v_mfma_f32_16x16x32_bf16 v[24:27], v[160:163], v[222:225], v[24:27]
	v_mfma_f32_16x16x32_bf16 v[12:15], v[142:145], v[230:233], v[12:15]
	v_mfma_f32_16x16x32_bf16 v[8:11], v[160:163], v[230:233], v[8:11]
	v_mfma_f32_16x16x32_bf16 v[52:55], v[164:167], v[180:183], v[52:55]
	v_mfma_f32_16x16x32_bf16 v[48:51], v[172:175], v[180:183], v[48:51]
	v_mfma_f32_16x16x32_bf16 v[36:39], v[164:167], v[188:191], v[36:39]
	v_mfma_f32_16x16x32_bf16 v[32:35], v[172:175], v[188:191], v[32:35]
	v_mfma_f32_16x16x32_bf16 v[20:23], v[164:167], v[218:221], v[20:23]
	v_mfma_f32_16x16x32_bf16 v[16:19], v[172:175], v[218:221], v[16:19]
	v_mfma_f32_16x16x32_bf16 v[4:7], v[164:167], v[226:229], v[4:7]
	v_mfma_f32_16x16x32_bf16 v[0:3], v[172:175], v[226:229], v[0:3]
	v_mfma_f32_16x16x32_bf16 v[52:55], v[168:171], v[184:187], v[52:55]
	v_mfma_f32_16x16x32_bf16 v[48:51], v[176:179], v[184:187], v[48:51]
	v_mfma_f32_16x16x32_bf16 v[36:39], v[168:171], v[198:201], v[36:39]
	v_mfma_f32_16x16x32_bf16 v[32:35], v[176:179], v[198:201], v[32:35]
	v_mfma_f32_16x16x32_bf16 v[20:23], v[168:171], v[222:225], v[20:23]
	v_mfma_f32_16x16x32_bf16 v[16:19], v[176:179], v[222:225], v[16:19]
	v_mfma_f32_16x16x32_bf16 v[4:7], v[168:171], v[230:233], v[4:7]
	v_mfma_f32_16x16x32_bf16 v[0:3], v[176:179], v[230:233], v[0:3]
	s_setprio 0
	s_barrier
	s_add_i32 s73, 0, 0x18000
	v_add_u32_e32 v146, s73, v155
	s_add_i32 s82, 0, 0x1c000
	ds_read_b128 v[128:131], v146
	ds_read_b128 v[142:145], v146 offset:1024
	ds_read_b128 v[150:153], v146 offset:2048
	ds_read_b128 v[160:163], v146 offset:3072
	v_add_u32_e32 v146, s82, v155
	ds_read_b128 v[164:167], v146
	ds_read_b128 v[168:171], v146 offset:1024
	ds_read_b128 v[172:175], v146 offset:2048
	ds_read_b128 v[176:179], v146 offset:3072
	s_add_u32 s24, s24, s8
	s_addc_u32 s25, s25, s9
	s_mov_b32 m0, s26
	v_lshl_add_u64 v[248:249], s[24:25], 0, v[136:137]
	ds_read_b128 v[180:183], v159 offset:32768
	ds_read_b128 v[184:187], v159 offset:33792
	ds_read_b128 v[188:191], v159 offset:34816
	ds_read_b128 v[198:201], v159 offset:35840
	ds_read_b128 v[218:221], v159 offset:36864
	ds_read_b128 v[222:225], v159 offset:37888
	ds_read_b128 v[226:229], v159 offset:38912
	ds_read_b128 v[230:233], v159 offset:39936
	global_load_lds_dwordx4 v[248:249], off
	v_lshl_add_u64 v[248:249], s[24:25], 0, v[134:135]
	s_mov_b32 m0, s30
	s_nop 0
	global_load_lds_dwordx4 v[248:249], off
	s_waitcnt vmcnt(8)
	s_waitcnt lgkmcnt(0)
	s_barrier
	s_setprio 1
	s_waitcnt lgkmcnt(0)
	v_mfma_f32_16x16x32_bf16 v[124:127], v[128:131], v[180:183], v[124:127]
	v_mfma_f32_16x16x32_bf16 v[120:123], v[150:153], v[180:183], v[120:123]
	v_mfma_f32_16x16x32_bf16 v[108:111], v[128:131], v[188:191], v[108:111]
	v_mfma_f32_16x16x32_bf16 v[104:107], v[150:153], v[188:191], v[104:107]
	v_mfma_f32_16x16x32_bf16 v[92:95], v[128:131], v[218:221], v[92:95]
	v_mfma_f32_16x16x32_bf16 v[88:91], v[150:153], v[218:221], v[88:91]
	v_mfma_f32_16x16x32_bf16 v[76:79], v[128:131], v[226:229], v[76:79]
	v_mfma_f32_16x16x32_bf16 v[72:75], v[150:153], v[226:229], v[72:75]
	v_mfma_f32_16x16x32_bf16 v[124:127], v[142:145], v[184:187], v[124:127]
	v_mfma_f32_16x16x32_bf16 v[120:123], v[160:163], v[184:187], v[120:123]
	v_mfma_f32_16x16x32_bf16 v[108:111], v[142:145], v[198:201], v[108:111]
	v_mfma_f32_16x16x32_bf16 v[104:107], v[160:163], v[198:201], v[104:107]
	v_mfma_f32_16x16x32_bf16 v[92:95], v[142:145], v[222:225], v[92:95]
	v_mfma_f32_16x16x32_bf16 v[88:91], v[160:163], v[222:225], v[88:91]
	v_mfma_f32_16x16x32_bf16 v[76:79], v[142:145], v[230:233], v[76:79]
	v_mfma_f32_16x16x32_bf16 v[72:75], v[160:163], v[230:233], v[72:75]
	v_mfma_f32_16x16x32_bf16 v[116:119], v[164:167], v[180:183], v[116:119]
	v_mfma_f32_16x16x32_bf16 v[112:115], v[172:175], v[180:183], v[112:115]
	v_mfma_f32_16x16x32_bf16 v[100:103], v[164:167], v[188:191], v[100:103]
	v_mfma_f32_16x16x32_bf16 v[96:99], v[172:175], v[188:191], v[96:99]
	v_mfma_f32_16x16x32_bf16 v[84:87], v[164:167], v[218:221], v[84:87]
	v_mfma_f32_16x16x32_bf16 v[80:83], v[172:175], v[218:221], v[80:83]
	v_mfma_f32_16x16x32_bf16 v[68:71], v[164:167], v[226:229], v[68:71]
	v_mfma_f32_16x16x32_bf16 v[64:67], v[172:175], v[226:229], v[64:67]
	v_mfma_f32_16x16x32_bf16 v[116:119], v[168:171], v[184:187], v[116:119]
	v_mfma_f32_16x16x32_bf16 v[112:115], v[176:179], v[184:187], v[112:115]
	v_mfma_f32_16x16x32_bf16 v[100:103], v[168:171], v[198:201], v[100:103]
	v_mfma_f32_16x16x32_bf16 v[96:99], v[176:179], v[198:201], v[96:99]
	v_mfma_f32_16x16x32_bf16 v[84:87], v[168:171], v[222:225], v[84:87]
	v_mfma_f32_16x16x32_bf16 v[80:83], v[176:179], v[222:225], v[80:83]
	v_mfma_f32_16x16x32_bf16 v[68:71], v[168:171], v[230:233], v[68:71]
	v_mfma_f32_16x16x32_bf16 v[64:67], v[176:179], v[230:233], v[64:67]
	s_setprio 0
	s_barrier
	s_add_i32 s24, s73, s7
	v_lshl_add_u64 v[156:157], v[156:157], 0, s[38:39]
	s_mov_b32 m0, s24
	ds_read_b128 v[180:183], v159 offset:49152
	ds_read_b128 v[184:187], v159 offset:50176
	ds_read_b128 v[188:191], v159 offset:51200
	ds_read_b128 v[198:201], v159 offset:52224
	ds_read_b128 v[218:221], v159 offset:53248
	ds_read_b128 v[222:225], v159 offset:54272
	ds_read_b128 v[226:229], v159 offset:55296
	ds_read_b128 v[230:233], v159 offset:56320
	global_load_lds_dwordx4 v[156:157], off
	v_lshl_add_u64 v[156:157], v[234:235], 0, s[38:39]
	s_add_i32 m0, s24, 0x2000
	s_add_i32 s24, s82, s7
	global_load_lds_dwordx4 v[156:157], off
	v_lshl_add_u64 v[156:157], v[236:237], 0, s[38:39]
	s_mov_b32 m0, s24
	s_nop 0
	global_load_lds_dwordx4 v[156:157], off
	v_lshl_add_u64 v[156:157], v[238:239], 0, s[38:39]
	s_add_i32 m0, s24, 0x2000
	s_nop 0
	global_load_lds_dwordx4 v[156:157], off
	v_lshl_add_u64 v[156:157], v[240:241], 0, s[38:39]
	s_mov_b32 m0, s42
	s_nop 0
	global_load_lds_dwordx4 v[156:157], off
	v_lshl_add_u64 v[156:157], v[246:247], 0, s[38:39]
	s_mov_b32 m0, s43
	s_nop 0
	global_load_lds_dwordx4 v[156:157], off
	s_waitcnt vmcnt(8)
	s_waitcnt lgkmcnt(0)
	s_barrier
	s_setprio 1
	s_waitcnt lgkmcnt(0)
	v_mfma_f32_16x16x32_bf16 v[60:63], v[128:131], v[180:183], v[60:63]
	v_mfma_f32_16x16x32_bf16 v[56:59], v[150:153], v[180:183], v[56:59]
	v_mfma_f32_16x16x32_bf16 v[44:47], v[128:131], v[188:191], v[44:47]
	v_mfma_f32_16x16x32_bf16 v[40:43], v[150:153], v[188:191], v[40:43]
	v_mfma_f32_16x16x32_bf16 v[28:31], v[128:131], v[218:221], v[28:31]
	v_mfma_f32_16x16x32_bf16 v[24:27], v[150:153], v[218:221], v[24:27]
	v_mfma_f32_16x16x32_bf16 v[12:15], v[128:131], v[226:229], v[12:15]
	v_mfma_f32_16x16x32_bf16 v[8:11], v[150:153], v[226:229], v[8:11]
	v_mfma_f32_16x16x32_bf16 v[60:63], v[142:145], v[184:187], v[60:63]
	v_mfma_f32_16x16x32_bf16 v[56:59], v[160:163], v[184:187], v[56:59]
	v_mfma_f32_16x16x32_bf16 v[44:47], v[142:145], v[198:201], v[44:47]
	v_mfma_f32_16x16x32_bf16 v[40:43], v[160:163], v[198:201], v[40:43]
	v_mfma_f32_16x16x32_bf16 v[28:31], v[142:145], v[222:225], v[28:31]
	v_mfma_f32_16x16x32_bf16 v[24:27], v[160:163], v[222:225], v[24:27]
	v_mfma_f32_16x16x32_bf16 v[12:15], v[142:145], v[230:233], v[12:15]
	v_mfma_f32_16x16x32_bf16 v[8:11], v[160:163], v[230:233], v[8:11]
	v_mfma_f32_16x16x32_bf16 v[52:55], v[164:167], v[180:183], v[52:55]
	v_mfma_f32_16x16x32_bf16 v[48:51], v[172:175], v[180:183], v[48:51]
	v_mfma_f32_16x16x32_bf16 v[36:39], v[164:167], v[188:191], v[36:39]
	v_mfma_f32_16x16x32_bf16 v[32:35], v[172:175], v[188:191], v[32:35]
	v_mfma_f32_16x16x32_bf16 v[20:23], v[164:167], v[218:221], v[20:23]
	v_mfma_f32_16x16x32_bf16 v[16:19], v[172:175], v[218:221], v[16:19]
	v_mfma_f32_16x16x32_bf16 v[4:7], v[164:167], v[226:229], v[4:7]
	v_mfma_f32_16x16x32_bf16 v[0:3], v[172:175], v[226:229], v[0:3]
	v_mfma_f32_16x16x32_bf16 v[52:55], v[168:171], v[184:187], v[52:55]
	v_mfma_f32_16x16x32_bf16 v[48:51], v[176:179], v[184:187], v[48:51]
	v_mfma_f32_16x16x32_bf16 v[36:39], v[168:171], v[198:201], v[36:39]
	v_mfma_f32_16x16x32_bf16 v[32:35], v[176:179], v[198:201], v[32:35]
	v_mfma_f32_16x16x32_bf16 v[20:23], v[168:171], v[222:225], v[20:23]
	v_mfma_f32_16x16x32_bf16 v[16:19], v[176:179], v[222:225], v[16:19]
	v_mfma_f32_16x16x32_bf16 v[4:7], v[168:171], v[230:233], v[4:7]
	v_mfma_f32_16x16x32_bf16 v[0:3], v[176:179], v[230:233], v[0:3]
	s_setprio 0
	s_barrier
	s_add_u32 s4, s4, 0x100
	s_addc_u32 s5, s5, 0
	s_add_u32 s28, s28, 0x100
	s_addc_u32 s29, s29, 0
	s_cmp_ge_i32 s72, s31
	s_mov_b32 s24, s72
	s_cbranch_scc0 .LBB0_782
	s_movk_i32 s83, 0x7f

.LBB0_1055:
	s_add_i32 s73, s28, 2
	s_add_u32 s82, s24, 0x80
	s_addc_u32 s29, s25, 0
	s_add_i32 s88, 0, 0x10000
	s_cmp_eq_u32 s43, s28
	s_cselect_b32 s29, s1, s29
	s_cselect_b32 s28, s0, s82
	s_cselect_b32 s83, s87, s72
	s_cselect_b32 s82, s86, s55
	s_add_i32 s89, 0, 0x14000
	v_add_u32_e32 v140, s88, v186
	v_add_u32_e32 v166, s89, v186
	ds_read_b128 v[128:131], v140
	ds_read_b128 v[132:135], v140 offset:1024
	ds_read_b128 v[136:139], v140 offset:2048
	ds_read_b128 v[140:143], v140 offset:3072
	ds_read_b128 v[144:147], v166
	ds_read_b128 v[148:151], v166 offset:1024
	ds_read_b128 v[152:155], v166 offset:2048
	ds_read_b128 v[166:169], v166 offset:3072
	v_lshl_add_u64 v[182:183], s[24:25], 0, v[162:163]
	s_add_i32 m0, s6, 0xc000
	ds_read_b128 v[170:173], v187
	ds_read_b128 v[174:177], v187 offset:1024
	ds_read_b128 v[178:181], v187 offset:2048
	ds_read_b128 v[188:191], v187 offset:3072
	ds_read_b128 v[198:201], v187 offset:4096
	ds_read_b128 v[218:221], v187 offset:5120
	ds_read_b128 v[222:225], v187 offset:6144
	ds_read_b128 v[226:229], v187 offset:7168
	global_load_lds_dwordx4 v[182:183], off
	v_lshl_add_u64 v[182:183], s[24:25], 0, v[164:165]
	s_add_i32 m0, s6, 0xe000
	s_nop 0
	global_load_lds_dwordx4 v[182:183], off
	s_waitcnt vmcnt(8)
	s_waitcnt lgkmcnt(0)
	s_barrier
	s_setprio 1
	s_waitcnt lgkmcnt(0)
	v_mfma_f32_16x16x32_bf16 v[120:123], v[128:131], v[170:173], v[120:123]
	v_mfma_f32_16x16x32_bf16 v[124:127], v[136:139], v[170:173], v[124:127]
	v_mfma_f32_16x16x32_bf16 v[108:111], v[128:131], v[178:181], v[108:111]
	v_mfma_f32_16x16x32_bf16 v[104:107], v[136:139], v[178:181], v[104:107]
	v_mfma_f32_16x16x32_bf16 v[92:95], v[128:131], v[198:201], v[92:95]
	v_mfma_f32_16x16x32_bf16 v[88:91], v[136:139], v[198:201], v[88:91]
	v_mfma_f32_16x16x32_bf16 v[76:79], v[128:131], v[222:225], v[76:79]
	v_mfma_f32_16x16x32_bf16 v[72:75], v[136:139], v[222:225], v[72:75]
	v_mfma_f32_16x16x32_bf16 v[120:123], v[132:135], v[174:177], v[120:123]
	v_mfma_f32_16x16x32_bf16 v[124:127], v[140:143], v[174:177], v[124:127]
	v_mfma_f32_16x16x32_bf16 v[108:111], v[132:135], v[188:191], v[108:111]
	v_mfma_f32_16x16x32_bf16 v[104:107], v[140:143], v[188:191], v[104:107]
	v_mfma_f32_16x16x32_bf16 v[92:95], v[132:135], v[218:221], v[92:95]
	v_mfma_f32_16x16x32_bf16 v[88:91], v[140:143], v[218:221], v[88:91]
	v_mfma_f32_16x16x32_bf16 v[76:79], v[132:135], v[226:229], v[76:79]
	v_mfma_f32_16x16x32_bf16 v[72:75], v[140:143], v[226:229], v[72:75]
	v_mfma_f32_16x16x32_bf16 v[116:119], v[144:147], v[170:173], v[116:119]
	v_mfma_f32_16x16x32_bf16 v[112:115], v[152:155], v[170:173], v[112:115]
	v_mfma_f32_16x16x32_bf16 v[100:103], v[144:147], v[178:181], v[100:103]
	v_mfma_f32_16x16x32_bf16 v[96:99], v[152:155], v[178:181], v[96:99]
	v_mfma_f32_16x16x32_bf16 v[84:87], v[144:147], v[198:201], v[84:87]
	v_mfma_f32_16x16x32_bf16 v[80:83], v[152:155], v[198:201], v[80:83]
	v_mfma_f32_16x16x32_bf16 v[68:71], v[144:147], v[222:225], v[68:71]
	v_mfma_f32_16x16x32_bf16 v[64:67], v[152:155], v[222:225], v[64:67]
	v_mfma_f32_16x16x32_bf16 v[116:119], v[148:151], v[174:177], v[116:119]
	v_mfma_f32_16x16x32_bf16 v[112:115], v[166:169], v[174:177], v[112:115]
	v_mfma_f32_16x16x32_bf16 v[100:103], v[148:151], v[188:191], v[100:103]
	v_mfma_f32_16x16x32_bf16 v[96:99], v[166:169], v[188:191], v[96:99]
	v_mfma_f32_16x16x32_bf16 v[84:87], v[148:151], v[218:221], v[84:87]
	v_mfma_f32_16x16x32_bf16 v[80:83], v[166:169], v[218:221], v[80:83]
	v_mfma_f32_16x16x32_bf16 v[68:71], v[148:151], v[226:229], v[68:71]
	v_mfma_f32_16x16x32_bf16 v[64:67], v[166:169], v[226:229], v[64:67]
	s_setprio 0
	s_barrier
	s_add_i32 s88, s88, s3
	v_lshl_add_u64 v[182:183], s[82:83], 0, v[194:195]
	s_mov_b32 m0, s88
	ds_read_b128 v[170:173], v187 offset:16384
	ds_read_b128 v[174:177], v187 offset:17408
	ds_read_b128 v[178:181], v187 offset:18432
	ds_read_b128 v[188:191], v187 offset:19456
	ds_read_b128 v[198:201], v187 offset:20480
	ds_read_b128 v[218:221], v187 offset:21504
	ds_read_b128 v[222:225], v187 offset:22528
	ds_read_b128 v[226:229], v187 offset:23552
	global_load_lds_dwordx4 v[182:183], off
	s_add_i32 m0, s88, 0x2000
	v_lshl_add_u64 v[230:231], s[82:83], 0, v[156:157]
	s_add_u32 s82, s82, s10
	s_addc_u32 s83, s83, s11
	s_add_i32 s88, s89, s3
	global_load_lds_dwordx4 v[230:231], off
	v_lshl_add_u64 v[232:233], s[82:83], 0, v[194:195]
	s_mov_b32 m0, s88
	v_lshl_add_u64 v[234:235], s[82:83], 0, v[156:157]
	global_load_lds_dwordx4 v[232:233], off
	s_add_i32 m0, s88, 0x2000
	v_lshl_add_u64 v[236:237], s[28:29], 0, v[160:161]
	global_load_lds_dwordx4 v[234:235], off
	s_mov_b32 m0, s6
	v_lshl_add_u64 v[238:239], s[28:29], 0, v[158:159]
	global_load_lds_dwordx4 v[236:237], off
	s_mov_b32 m0, s7
	s_nop 0
	global_load_lds_dwordx4 v[238:239], off
	s_waitcnt vmcnt(8)
	s_waitcnt lgkmcnt(0)
	s_barrier
	s_setprio 1
	s_waitcnt lgkmcnt(0)
	v_mfma_f32_16x16x32_bf16 v[60:63], v[128:131], v[170:173], v[60:63]
	v_mfma_f32_16x16x32_bf16 v[56:59], v[136:139], v[170:173], v[56:59]
	v_mfma_f32_16x16x32_bf16 v[44:47], v[128:131], v[178:181], v[44:47]
	v_mfma_f32_16x16x32_bf16 v[40:43], v[136:139], v[178:181], v[40:43]
	v_mfma_f32_16x16x32_bf16 v[28:31], v[128:131], v[198:201], v[28:31]
	v_mfma_f32_16x16x32_bf16 v[24:27], v[136:139], v[198:201], v[24:27]
	v_mfma_f32_16x16x32_bf16 v[12:15], v[128:131], v[222:225], v[12:15]
	v_mfma_f32_16x16x32_bf16 v[8:11], v[136:139], v[222:225], v[8:11]
	v_mfma_f32_16x16x32_bf16 v[60:63], v[132:135], v[174:177], v[60:63]
	v_mfma_f32_16x16x32_bf16 v[56:59], v[140:143], v[174:177], v[56:59]
	v_mfma_f32_16x16x32_bf16 v[44:47], v[132:135], v[188:191], v[44:47]
	v_mfma_f32_16x16x32_bf16 v[40:43], v[140:143], v[188:191], v[40:43]
	v_mfma_f32_16x16x32_bf16 v[28:31], v[132:135], v[218:221], v[28:31]
	v_mfma_f32_16x16x32_bf16 v[24:27], v[140:143], v[218:221], v[24:27]
	v_mfma_f32_16x16x32_bf16 v[12:15], v[132:135], v[226:229], v[12:15]
	v_mfma_f32_16x16x32_bf16 v[8:11], v[140:143], v[226:229], v[8:11]
	v_mfma_f32_16x16x32_bf16 v[52:55], v[144:147], v[170:173], v[52:55]
	v_mfma_f32_16x16x32_bf16 v[48:51], v[152:155], v[170:173], v[48:51]
	v_mfma_f32_16x16x32_bf16 v[36:39], v[144:147], v[178:181], v[36:39]
	v_mfma_f32_16x16x32_bf16 v[32:35], v[152:155], v[178:181], v[32:35]
	v_mfma_f32_16x16x32_bf16 v[20:23], v[144:147], v[198:201], v[20:23]
	v_mfma_f32_16x16x32_bf16 v[16:19], v[152:155], v[198:201], v[16:19]
	v_mfma_f32_16x16x32_bf16 v[4:7], v[144:147], v[222:225], v[4:7]
	v_mfma_f32_16x16x32_bf16 v[0:3], v[152:155], v[222:225], v[0:3]
	v_mfma_f32_16x16x32_bf16 v[52:55], v[148:151], v[174:177], v[52:55]
	v_mfma_f32_16x16x32_bf16 v[48:51], v[166:169], v[174:177], v[48:51]
	v_mfma_f32_16x16x32_bf16 v[36:39], v[148:151], v[188:191], v[36:39]
	v_mfma_f32_16x16x32_bf16 v[32:35], v[166:169], v[188:191], v[32:35]
	v_mfma_f32_16x16x32_bf16 v[20:23], v[148:151], v[218:221], v[20:23]
	v_mfma_f32_16x16x32_bf16 v[16:19], v[166:169], v[218:221], v[16:19]
	v_mfma_f32_16x16x32_bf16 v[4:7], v[148:151], v[226:229], v[4:7]
	v_mfma_f32_16x16x32_bf16 v[0:3], v[166:169], v[226:229], v[0:3]
	s_setprio 0
	s_barrier
	s_add_i32 s82, 0, 0x18000
	s_add_i32 s83, 0, 0x1c000
	v_add_u32_e32 v140, s82, v186
	v_add_u32_e32 v166, s83, v186
	ds_read_b128 v[128:131], v140
	ds_read_b128 v[132:135], v140 offset:1024
	ds_read_b128 v[136:139], v140 offset:2048
	ds_read_b128 v[140:143], v140 offset:3072
	ds_read_b128 v[144:147], v166
	ds_read_b128 v[148:151], v166 offset:1024
	ds_read_b128 v[152:155], v166 offset:2048
	ds_read_b128 v[166:169], v166 offset:3072
	s_add_u32 s28, s28, s10
	s_addc_u32 s29, s29, s11
	s_mov_b32 m0, s16
	v_lshl_add_u64 v[240:241], s[28:29], 0, v[160:161]
	ds_read_b128 v[170:173], v187 offset:32768
	ds_read_b128 v[174:177], v187 offset:33792
	ds_read_b128 v[178:181], v187 offset:34816
	ds_read_b128 v[188:191], v187 offset:35840
	ds_read_b128 v[198:201], v187 offset:36864
	ds_read_b128 v[218:221], v187 offset:37888
	ds_read_b128 v[222:225], v187 offset:38912
	ds_read_b128 v[226:229], v187 offset:39936
	global_load_lds_dwordx4 v[240:241], off
	v_lshl_add_u64 v[240:241], s[28:29], 0, v[158:159]
	s_mov_b32 m0, s20
	s_nop 0
	global_load_lds_dwordx4 v[240:241], off
	s_waitcnt vmcnt(8)
	s_waitcnt lgkmcnt(0)
	s_barrier
	s_setprio 1
	s_waitcnt lgkmcnt(0)
	v_mfma_f32_16x16x32_bf16 v[120:123], v[128:131], v[170:173], v[120:123]
	v_mfma_f32_16x16x32_bf16 v[124:127], v[136:139], v[170:173], v[124:127]
	v_mfma_f32_16x16x32_bf16 v[108:111], v[128:131], v[178:181], v[108:111]
	v_mfma_f32_16x16x32_bf16 v[104:107], v[136:139], v[178:181], v[104:107]
	v_mfma_f32_16x16x32_bf16 v[92:95], v[128:131], v[198:201], v[92:95]
	v_mfma_f32_16x16x32_bf16 v[88:91], v[136:139], v[198:201], v[88:91]
	v_mfma_f32_16x16x32_bf16 v[76:79], v[128:131], v[222:225], v[76:79]
	v_mfma_f32_16x16x32_bf16 v[72:75], v[136:139], v[222:225], v[72:75]
	v_mfma_f32_16x16x32_bf16 v[120:123], v[132:135], v[174:177], v[120:123]
	v_mfma_f32_16x16x32_bf16 v[124:127], v[140:143], v[174:177], v[124:127]
	v_mfma_f32_16x16x32_bf16 v[108:111], v[132:135], v[188:191], v[108:111]
	v_mfma_f32_16x16x32_bf16 v[104:107], v[140:143], v[188:191], v[104:107]
	v_mfma_f32_16x16x32_bf16 v[92:95], v[132:135], v[218:221], v[92:95]
	v_mfma_f32_16x16x32_bf16 v[88:91], v[140:143], v[218:221], v[88:91]
	v_mfma_f32_16x16x32_bf16 v[76:79], v[132:135], v[226:229], v[76:79]
	v_mfma_f32_16x16x32_bf16 v[72:75], v[140:143], v[226:229], v[72:75]
	v_mfma_f32_16x16x32_bf16 v[116:119], v[144:147], v[170:173], v[116:119]
	v_mfma_f32_16x16x32_bf16 v[112:115], v[152:155], v[170:173], v[112:115]
	v_mfma_f32_16x16x32_bf16 v[100:103], v[144:147], v[178:181], v[100:103]
	v_mfma_f32_16x16x32_bf16 v[96:99], v[152:155], v[178:181], v[96:99]
	v_mfma_f32_16x16x32_bf16 v[84:87], v[144:147], v[198:201], v[84:87]
	v_mfma_f32_16x16x32_bf16 v[80:83], v[152:155], v[198:201], v[80:83]
	v_mfma_f32_16x16x32_bf16 v[68:71], v[144:147], v[222:225], v[68:71]
	v_mfma_f32_16x16x32_bf16 v[64:67], v[152:155], v[222:225], v[64:67]
	v_mfma_f32_16x16x32_bf16 v[116:119], v[148:151], v[174:177], v[116:119]
	v_mfma_f32_16x16x32_bf16 v[112:115], v[166:169], v[174:177], v[112:115]
	v_mfma_f32_16x16x32_bf16 v[100:103], v[148:151], v[188:191], v[100:103]
	v_mfma_f32_16x16x32_bf16 v[96:99], v[166:169], v[188:191], v[96:99]
	v_mfma_f32_16x16x32_bf16 v[84:87], v[148:151], v[218:221], v[84:87]
	v_mfma_f32_16x16x32_bf16 v[80:83], v[166:169], v[218:221], v[80:83]
	v_mfma_f32_16x16x32_bf16 v[68:71], v[148:151], v[226:229], v[68:71]
	v_mfma_f32_16x16x32_bf16 v[64:67], v[166:169], v[226:229], v[64:67]
	s_setprio 0
	s_barrier
	s_add_i32 s28, s82, s3
	v_lshl_add_u64 v[182:183], v[182:183], 0, s[38:39]
	s_mov_b32 m0, s28
	ds_read_b128 v[170:173], v187 offset:49152
	ds_read_b128 v[174:177], v187 offset:50176
	ds_read_b128 v[178:181], v187 offset:51200
	ds_read_b128 v[188:191], v187 offset:52224
	ds_read_b128 v[198:201], v187 offset:53248
	ds_read_b128 v[218:221], v187 offset:54272
	ds_read_b128 v[222:225], v187 offset:55296
	ds_read_b128 v[226:229], v187 offset:56320
	global_load_lds_dwordx4 v[182:183], off
	v_lshl_add_u64 v[182:183], v[230:231], 0, s[38:39]
	s_add_i32 m0, s28, 0x2000
	s_add_i32 s28, s83, s3
	global_load_lds_dwordx4 v[182:183], off
	v_lshl_add_u64 v[182:183], v[232:233], 0, s[38:39]
	s_mov_b32 m0, s28
	s_nop 0
	global_load_lds_dwordx4 v[182:183], off
	v_lshl_add_u64 v[182:183], v[234:235], 0, s[38:39]
	s_add_i32 m0, s28, 0x2000
	s_nop 0
	global_load_lds_dwordx4 v[182:183], off
	v_lshl_add_u64 v[182:183], v[236:237], 0, s[38:39]
	s_mov_b32 m0, s35
	s_nop 0
	global_load_lds_dwordx4 v[182:183], off
	v_lshl_add_u64 v[182:183], v[238:239], 0, s[38:39]
	s_mov_b32 m0, s42
	s_nop 0
	global_load_lds_dwordx4 v[182:183], off
	s_waitcnt vmcnt(8)
	s_waitcnt lgkmcnt(0)
	s_barrier
	s_setprio 1
	s_waitcnt lgkmcnt(0)
	v_mfma_f32_16x16x32_bf16 v[60:63], v[128:131], v[170:173], v[60:63]
	v_mfma_f32_16x16x32_bf16 v[56:59], v[136:139], v[170:173], v[56:59]
	v_mfma_f32_16x16x32_bf16 v[44:47], v[128:131], v[178:181], v[44:47]
	v_mfma_f32_16x16x32_bf16 v[40:43], v[136:139], v[178:181], v[40:43]
	v_mfma_f32_16x16x32_bf16 v[28:31], v[128:131], v[198:201], v[28:31]
	v_mfma_f32_16x16x32_bf16 v[24:27], v[136:139], v[198:201], v[24:27]
	v_mfma_f32_16x16x32_bf16 v[12:15], v[128:131], v[222:225], v[12:15]
	v_mfma_f32_16x16x32_bf16 v[8:11], v[136:139], v[222:225], v[8:11]
	v_mfma_f32_16x16x32_bf16 v[60:63], v[132:135], v[174:177], v[60:63]
	v_mfma_f32_16x16x32_bf16 v[56:59], v[140:143], v[174:177], v[56:59]
	v_mfma_f32_16x16x32_bf16 v[44:47], v[132:135], v[188:191], v[44:47]
	v_mfma_f32_16x16x32_bf16 v[40:43], v[140:143], v[188:191], v[40:43]
	v_mfma_f32_16x16x32_bf16 v[28:31], v[132:135], v[218:221], v[28:31]
	v_mfma_f32_16x16x32_bf16 v[24:27], v[140:143], v[218:221], v[24:27]
	v_mfma_f32_16x16x32_bf16 v[12:15], v[132:135], v[226:229], v[12:15]
	v_mfma_f32_16x16x32_bf16 v[8:11], v[140:143], v[226:229], v[8:11]
	v_mfma_f32_16x16x32_bf16 v[52:55], v[144:147], v[170:173], v[52:55]
	v_mfma_f32_16x16x32_bf16 v[48:51], v[152:155], v[170:173], v[48:51]
	v_mfma_f32_16x16x32_bf16 v[36:39], v[144:147], v[178:181], v[36:39]
	v_mfma_f32_16x16x32_bf16 v[32:35], v[152:155], v[178:181], v[32:35]
	v_mfma_f32_16x16x32_bf16 v[20:23], v[144:147], v[198:201], v[20:23]
	v_mfma_f32_16x16x32_bf16 v[16:19], v[152:155], v[198:201], v[16:19]
	v_mfma_f32_16x16x32_bf16 v[4:7], v[144:147], v[222:225], v[4:7]
	v_mfma_f32_16x16x32_bf16 v[0:3], v[152:155], v[222:225], v[0:3]
	v_mfma_f32_16x16x32_bf16 v[52:55], v[148:151], v[174:177], v[52:55]
	v_mfma_f32_16x16x32_bf16 v[48:51], v[166:169], v[174:177], v[48:51]
	v_mfma_f32_16x16x32_bf16 v[36:39], v[148:151], v[188:191], v[36:39]
	v_mfma_f32_16x16x32_bf16 v[32:35], v[166:169], v[188:191], v[32:35]
	v_mfma_f32_16x16x32_bf16 v[20:23], v[148:151], v[218:221], v[20:23]
	v_mfma_f32_16x16x32_bf16 v[16:19], v[166:169], v[218:221], v[16:19]
	v_mfma_f32_16x16x32_bf16 v[4:7], v[148:151], v[226:229], v[4:7]
	v_mfma_f32_16x16x32_bf16 v[0:3], v[166:169], v[226:229], v[0:3]
	s_setprio 0
	s_barrier
	s_add_u32 s24, s24, 0x100
	s_addc_u32 s25, s25, 0
	s_add_u32 s55, s55, 0x100
	s_addc_u32 s72, s72, 0
	s_cmp_ge_i32 s73, s30
	s_mov_b32 s28, s73
	s_cbranch_scc0 .LBB0_1055
	s_movk_i32 s83, 0x7f

.LBB0_1149:
	s_add_i32 s82, s30, 2
	s_add_u32 s83, s28, 0x80
	s_addc_u32 s31, s29, 0
	s_add_i32 s88, 0, 0x10000
	s_cmp_eq_u32 s54, s30
	s_cselect_b32 s31, s5, s31
	s_cselect_b32 s30, s4, s83
	v_add_u32_e32 v138, s88, v142
	s_cselect_b32 s87, s25, s49
	s_cselect_b32 s86, s24, s48
	s_add_i32 s83, 0, 0x14000
	ds_read_b128 v[144:147], v138
	ds_read_b128 v[148:151], v138 offset:1024
	ds_read_b128 v[152:155], v138 offset:2048
	ds_read_b128 v[156:159], v138 offset:3072
	v_add_u32_e32 v138, s83, v142
	ds_read_b128 v[160:163], v138
	ds_read_b128 v[164:167], v138 offset:1024
	ds_read_b128 v[168:171], v138 offset:2048
	ds_read_b128 v[172:175], v138 offset:3072
	v_lshl_add_u64 v[138:139], s[28:29], 0, v[134:135]
	s_add_i32 m0, s16, 0xc000
	ds_read_b128 v[176:179], v143
	ds_read_b128 v[180:183], v143 offset:1024
	ds_read_b128 v[184:187], v143 offset:2048
	ds_read_b128 v[188:191], v143 offset:3072
	ds_read_b128 v[198:201], v143 offset:4096
	ds_read_b128 v[218:221], v143 offset:5120
	ds_read_b128 v[222:225], v143 offset:6144
	ds_read_b128 v[226:229], v143 offset:7168
	global_load_lds_dwordx4 v[138:139], off
	v_lshl_add_u64 v[138:139], s[28:29], 0, v[136:137]
	s_add_i32 m0, s16, 0xe000
	s_nop 0
	global_load_lds_dwordx4 v[138:139], off
	s_waitcnt vmcnt(8)
	s_waitcnt lgkmcnt(0)
	s_barrier
	s_setprio 1
	s_waitcnt lgkmcnt(0)
	v_mfma_f32_16x16x32_bf16 v[120:123], v[144:147], v[176:179], v[120:123]
	v_mfma_f32_16x16x32_bf16 v[124:127], v[152:155], v[176:179], v[124:127]
	v_mfma_f32_16x16x32_bf16 v[108:111], v[144:147], v[184:187], v[108:111]
	v_mfma_f32_16x16x32_bf16 v[104:107], v[152:155], v[184:187], v[104:107]
	v_mfma_f32_16x16x32_bf16 v[92:95], v[144:147], v[198:201], v[92:95]
	v_mfma_f32_16x16x32_bf16 v[88:91], v[152:155], v[198:201], v[88:91]
	v_mfma_f32_16x16x32_bf16 v[76:79], v[144:147], v[222:225], v[76:79]
	v_mfma_f32_16x16x32_bf16 v[72:75], v[152:155], v[222:225], v[72:75]
	v_mfma_f32_16x16x32_bf16 v[120:123], v[148:151], v[180:183], v[120:123]
	v_mfma_f32_16x16x32_bf16 v[124:127], v[156:159], v[180:183], v[124:127]
	v_mfma_f32_16x16x32_bf16 v[108:111], v[148:151], v[188:191], v[108:111]
	v_mfma_f32_16x16x32_bf16 v[104:107], v[156:159], v[188:191], v[104:107]
	v_mfma_f32_16x16x32_bf16 v[92:95], v[148:151], v[218:221], v[92:95]
	v_mfma_f32_16x16x32_bf16 v[88:91], v[156:159], v[218:221], v[88:91]
	v_mfma_f32_16x16x32_bf16 v[76:79], v[148:151], v[226:229], v[76:79]
	v_mfma_f32_16x16x32_bf16 v[72:75], v[156:159], v[226:229], v[72:75]
	v_mfma_f32_16x16x32_bf16 v[116:119], v[160:163], v[176:179], v[116:119]
	v_mfma_f32_16x16x32_bf16 v[112:115], v[168:171], v[176:179], v[112:115]
	v_mfma_f32_16x16x32_bf16 v[100:103], v[160:163], v[184:187], v[100:103]
	v_mfma_f32_16x16x32_bf16 v[96:99], v[168:171], v[184:187], v[96:99]
	v_mfma_f32_16x16x32_bf16 v[84:87], v[160:163], v[198:201], v[84:87]
	v_mfma_f32_16x16x32_bf16 v[80:83], v[168:171], v[198:201], v[80:83]
	v_mfma_f32_16x16x32_bf16 v[68:71], v[160:163], v[222:225], v[68:71]
	v_mfma_f32_16x16x32_bf16 v[64:67], v[168:171], v[222:225], v[64:67]
	v_mfma_f32_16x16x32_bf16 v[116:119], v[164:167], v[180:183], v[116:119]
	v_mfma_f32_16x16x32_bf16 v[112:115], v[172:175], v[180:183], v[112:115]
	v_mfma_f32_16x16x32_bf16 v[100:103], v[164:167], v[188:191], v[100:103]
	v_mfma_f32_16x16x32_bf16 v[96:99], v[172:175], v[188:191], v[96:99]
	v_mfma_f32_16x16x32_bf16 v[84:87], v[164:167], v[218:221], v[84:87]
	v_mfma_f32_16x16x32_bf16 v[80:83], v[172:175], v[218:221], v[80:83]
	v_mfma_f32_16x16x32_bf16 v[68:71], v[164:167], v[226:229], v[68:71]
	v_mfma_f32_16x16x32_bf16 v[64:67], v[172:175], v[226:229], v[64:67]
	s_setprio 0
	s_barrier
	s_add_i32 s88, s88, s7
	v_lshl_add_u64 v[138:139], s[86:87], 0, v[194:195]
	s_mov_b32 m0, s88
	ds_read_b128 v[176:179], v143 offset:16384
	ds_read_b128 v[180:183], v143 offset:17408
	ds_read_b128 v[184:187], v143 offset:18432
	ds_read_b128 v[188:191], v143 offset:19456
	ds_read_b128 v[198:201], v143 offset:20480
	ds_read_b128 v[218:221], v143 offset:21504
	ds_read_b128 v[222:225], v143 offset:22528
	ds_read_b128 v[226:229], v143 offset:23552
	global_load_lds_dwordx4 v[138:139], off
	s_add_i32 m0, s88, 0x2000
	v_lshl_add_u64 v[230:231], s[86:87], 0, v[128:129]
	s_add_u32 s86, s86, s8
	s_addc_u32 s87, s87, s9
	s_add_i32 s83, s83, s7
	global_load_lds_dwordx4 v[230:231], off
	v_lshl_add_u64 v[232:233], s[86:87], 0, v[194:195]
	s_mov_b32 m0, s83
	v_lshl_add_u64 v[234:235], s[86:87], 0, v[128:129]
	global_load_lds_dwordx4 v[232:233], off
	s_add_i32 m0, s83, 0x2000
	v_lshl_add_u64 v[236:237], s[30:31], 0, v[132:133]
	global_load_lds_dwordx4 v[234:235], off
	s_mov_b32 m0, s16
	v_lshl_add_u64 v[238:239], s[30:31], 0, v[130:131]
	global_load_lds_dwordx4 v[236:237], off
	s_mov_b32 m0, s20
	s_nop 0
	global_load_lds_dwordx4 v[238:239], off
	s_waitcnt vmcnt(8)
	s_waitcnt lgkmcnt(0)
	s_barrier
	s_setprio 1
	s_waitcnt lgkmcnt(0)
	v_mfma_f32_16x16x32_bf16 v[60:63], v[144:147], v[176:179], v[60:63]
	v_mfma_f32_16x16x32_bf16 v[56:59], v[152:155], v[176:179], v[56:59]
	v_mfma_f32_16x16x32_bf16 v[44:47], v[144:147], v[184:187], v[44:47]
	v_mfma_f32_16x16x32_bf16 v[40:43], v[152:155], v[184:187], v[40:43]
	v_mfma_f32_16x16x32_bf16 v[28:31], v[144:147], v[198:201], v[28:31]
	v_mfma_f32_16x16x32_bf16 v[24:27], v[152:155], v[198:201], v[24:27]
	v_mfma_f32_16x16x32_bf16 v[12:15], v[144:147], v[222:225], v[12:15]
	v_mfma_f32_16x16x32_bf16 v[8:11], v[152:155], v[222:225], v[8:11]
	v_mfma_f32_16x16x32_bf16 v[60:63], v[148:151], v[180:183], v[60:63]
	v_mfma_f32_16x16x32_bf16 v[56:59], v[156:159], v[180:183], v[56:59]
	v_mfma_f32_16x16x32_bf16 v[44:47], v[148:151], v[188:191], v[44:47]
	v_mfma_f32_16x16x32_bf16 v[40:43], v[156:159], v[188:191], v[40:43]
	v_mfma_f32_16x16x32_bf16 v[28:31], v[148:151], v[218:221], v[28:31]
	v_mfma_f32_16x16x32_bf16 v[24:27], v[156:159], v[218:221], v[24:27]
	v_mfma_f32_16x16x32_bf16 v[12:15], v[148:151], v[226:229], v[12:15]
	v_mfma_f32_16x16x32_bf16 v[8:11], v[156:159], v[226:229], v[8:11]
	v_mfma_f32_16x16x32_bf16 v[52:55], v[160:163], v[176:179], v[52:55]
	v_mfma_f32_16x16x32_bf16 v[48:51], v[168:171], v[176:179], v[48:51]
	v_mfma_f32_16x16x32_bf16 v[36:39], v[160:163], v[184:187], v[36:39]
	v_mfma_f32_16x16x32_bf16 v[32:35], v[168:171], v[184:187], v[32:35]
	v_mfma_f32_16x16x32_bf16 v[20:23], v[160:163], v[198:201], v[20:23]
	v_mfma_f32_16x16x32_bf16 v[16:19], v[168:171], v[198:201], v[16:19]
	v_mfma_f32_16x16x32_bf16 v[4:7], v[160:163], v[222:225], v[4:7]
	v_mfma_f32_16x16x32_bf16 v[0:3], v[168:171], v[222:225], v[0:3]
	v_mfma_f32_16x16x32_bf16 v[52:55], v[164:167], v[180:183], v[52:55]
	v_mfma_f32_16x16x32_bf16 v[48:51], v[172:175], v[180:183], v[48:51]
	v_mfma_f32_16x16x32_bf16 v[36:39], v[164:167], v[188:191], v[36:39]
	v_mfma_f32_16x16x32_bf16 v[32:35], v[172:175], v[188:191], v[32:35]
	v_mfma_f32_16x16x32_bf16 v[20:23], v[164:167], v[218:221], v[20:23]
	v_mfma_f32_16x16x32_bf16 v[16:19], v[172:175], v[218:221], v[16:19]
	v_mfma_f32_16x16x32_bf16 v[4:7], v[164:167], v[226:229], v[4:7]
	v_mfma_f32_16x16x32_bf16 v[0:3], v[172:175], v[226:229], v[0:3]
	s_setprio 0
	s_barrier
	s_add_i32 s83, 0, 0x18000
	s_add_i32 s86, 0, 0x1c000
	v_add_u32_e32 v156, s83, v142
	v_add_u32_e32 v172, s86, v142
	ds_read_b128 v[144:147], v156
	ds_read_b128 v[148:151], v156 offset:1024
	ds_read_b128 v[152:155], v156 offset:2048
	ds_read_b128 v[156:159], v156 offset:3072
	ds_read_b128 v[160:163], v172
	ds_read_b128 v[164:167], v172 offset:1024
	ds_read_b128 v[168:171], v172 offset:2048
	ds_read_b128 v[172:175], v172 offset:3072
	s_add_u32 s30, s30, s8
	s_addc_u32 s31, s31, s9
	s_mov_b32 m0, s26
	v_lshl_add_u64 v[240:241], s[30:31], 0, v[132:133]
	ds_read_b128 v[176:179], v143 offset:32768
	ds_read_b128 v[180:183], v143 offset:33792
	ds_read_b128 v[184:187], v143 offset:34816
	ds_read_b128 v[188:191], v143 offset:35840
	ds_read_b128 v[198:201], v143 offset:36864
	ds_read_b128 v[218:221], v143 offset:37888
	ds_read_b128 v[222:225], v143 offset:38912
	ds_read_b128 v[226:229], v143 offset:39936
	global_load_lds_dwordx4 v[240:241], off
	v_lshl_add_u64 v[240:241], s[30:31], 0, v[130:131]
	s_mov_b32 m0, s33
	s_nop 0
	global_load_lds_dwordx4 v[240:241], off
	s_waitcnt vmcnt(8)
	s_waitcnt lgkmcnt(0)
	s_barrier
	s_setprio 1
	s_waitcnt lgkmcnt(0)
	v_mfma_f32_16x16x32_bf16 v[120:123], v[144:147], v[176:179], v[120:123]
	v_mfma_f32_16x16x32_bf16 v[124:127], v[152:155], v[176:179], v[124:127]
	v_mfma_f32_16x16x32_bf16 v[108:111], v[144:147], v[184:187], v[108:111]
	v_mfma_f32_16x16x32_bf16 v[104:107], v[152:155], v[184:187], v[104:107]
	v_mfma_f32_16x16x32_bf16 v[92:95], v[144:147], v[198:201], v[92:95]
	v_mfma_f32_16x16x32_bf16 v[88:91], v[152:155], v[198:201], v[88:91]
	v_mfma_f32_16x16x32_bf16 v[76:79], v[144:147], v[222:225], v[76:79]
	v_mfma_f32_16x16x32_bf16 v[72:75], v[152:155], v[222:225], v[72:75]
	v_mfma_f32_16x16x32_bf16 v[120:123], v[148:151], v[180:183], v[120:123]
	v_mfma_f32_16x16x32_bf16 v[124:127], v[156:159], v[180:183], v[124:127]
	v_mfma_f32_16x16x32_bf16 v[108:111], v[148:151], v[188:191], v[108:111]
	v_mfma_f32_16x16x32_bf16 v[104:107], v[156:159], v[188:191], v[104:107]
	v_mfma_f32_16x16x32_bf16 v[92:95], v[148:151], v[218:221], v[92:95]
	v_mfma_f32_16x16x32_bf16 v[88:91], v[156:159], v[218:221], v[88:91]
	v_mfma_f32_16x16x32_bf16 v[76:79], v[148:151], v[226:229], v[76:79]
	v_mfma_f32_16x16x32_bf16 v[72:75], v[156:159], v[226:229], v[72:75]
	v_mfma_f32_16x16x32_bf16 v[116:119], v[160:163], v[176:179], v[116:119]
	v_mfma_f32_16x16x32_bf16 v[112:115], v[168:171], v[176:179], v[112:115]
	v_mfma_f32_16x16x32_bf16 v[100:103], v[160:163], v[184:187], v[100:103]
	v_mfma_f32_16x16x32_bf16 v[96:99], v[168:171], v[184:187], v[96:99]
	v_mfma_f32_16x16x32_bf16 v[84:87], v[160:163], v[198:201], v[84:87]
	v_mfma_f32_16x16x32_bf16 v[80:83], v[168:171], v[198:201], v[80:83]
	v_mfma_f32_16x16x32_bf16 v[68:71], v[160:163], v[222:225], v[68:71]
	v_mfma_f32_16x16x32_bf16 v[64:67], v[168:171], v[222:225], v[64:67]
	v_mfma_f32_16x16x32_bf16 v[116:119], v[164:167], v[180:183], v[116:119]
	v_mfma_f32_16x16x32_bf16 v[112:115], v[172:175], v[180:183], v[112:115]
	v_mfma_f32_16x16x32_bf16 v[100:103], v[164:167], v[188:191], v[100:103]
	v_mfma_f32_16x16x32_bf16 v[96:99], v[172:175], v[188:191], v[96:99]
	v_mfma_f32_16x16x32_bf16 v[84:87], v[164:167], v[218:221], v[84:87]
	v_mfma_f32_16x16x32_bf16 v[80:83], v[172:175], v[218:221], v[80:83]
	v_mfma_f32_16x16x32_bf16 v[68:71], v[164:167], v[226:229], v[68:71]
	v_mfma_f32_16x16x32_bf16 v[64:67], v[172:175], v[226:229], v[64:67]
	s_setprio 0
	s_barrier
	s_add_i32 s30, s83, s7
	v_lshl_add_u64 v[138:139], v[138:139], 0, s[38:39]
	s_mov_b32 m0, s30
	ds_read_b128 v[176:179], v143 offset:49152
	ds_read_b128 v[180:183], v143 offset:50176
	ds_read_b128 v[184:187], v143 offset:51200
	ds_read_b128 v[188:191], v143 offset:52224
	ds_read_b128 v[198:201], v143 offset:53248
	ds_read_b128 v[218:221], v143 offset:54272
	ds_read_b128 v[222:225], v143 offset:55296
	ds_read_b128 v[226:229], v143 offset:56320
	global_load_lds_dwordx4 v[138:139], off
	v_lshl_add_u64 v[138:139], v[230:231], 0, s[38:39]
	s_add_i32 m0, s30, 0x2000
	s_add_i32 s30, s86, s7
	global_load_lds_dwordx4 v[138:139], off
	v_lshl_add_u64 v[138:139], v[232:233], 0, s[38:39]
	s_mov_b32 m0, s30
	s_nop 0
	global_load_lds_dwordx4 v[138:139], off
	v_lshl_add_u64 v[138:139], v[234:235], 0, s[38:39]
	s_add_i32 m0, s30, 0x2000
	s_nop 0
	global_load_lds_dwordx4 v[138:139], off
	v_lshl_add_u64 v[138:139], v[236:237], 0, s[38:39]
	s_mov_b32 m0, s50
	s_nop 0
	global_load_lds_dwordx4 v[138:139], off
	v_lshl_add_u64 v[138:139], v[238:239], 0, s[38:39]
	s_mov_b32 m0, s51
	s_nop 0
	global_load_lds_dwordx4 v[138:139], off
	s_waitcnt vmcnt(8)
	s_waitcnt lgkmcnt(0)
	s_barrier
	s_setprio 1
	s_waitcnt lgkmcnt(0)
	v_mfma_f32_16x16x32_bf16 v[60:63], v[144:147], v[176:179], v[60:63]
	v_mfma_f32_16x16x32_bf16 v[56:59], v[152:155], v[176:179], v[56:59]
	v_mfma_f32_16x16x32_bf16 v[44:47], v[144:147], v[184:187], v[44:47]
	v_mfma_f32_16x16x32_bf16 v[40:43], v[152:155], v[184:187], v[40:43]
	v_mfma_f32_16x16x32_bf16 v[28:31], v[144:147], v[198:201], v[28:31]
	v_mfma_f32_16x16x32_bf16 v[24:27], v[152:155], v[198:201], v[24:27]
	v_mfma_f32_16x16x32_bf16 v[12:15], v[144:147], v[222:225], v[12:15]
	v_mfma_f32_16x16x32_bf16 v[8:11], v[152:155], v[222:225], v[8:11]
	v_mfma_f32_16x16x32_bf16 v[60:63], v[148:151], v[180:183], v[60:63]
	v_mfma_f32_16x16x32_bf16 v[56:59], v[156:159], v[180:183], v[56:59]
	v_mfma_f32_16x16x32_bf16 v[44:47], v[148:151], v[188:191], v[44:47]
	v_mfma_f32_16x16x32_bf16 v[40:43], v[156:159], v[188:191], v[40:43]
	v_mfma_f32_16x16x32_bf16 v[28:31], v[148:151], v[218:221], v[28:31]
	v_mfma_f32_16x16x32_bf16 v[24:27], v[156:159], v[218:221], v[24:27]
	v_mfma_f32_16x16x32_bf16 v[12:15], v[148:151], v[226:229], v[12:15]
	v_mfma_f32_16x16x32_bf16 v[8:11], v[156:159], v[226:229], v[8:11]
	v_mfma_f32_16x16x32_bf16 v[52:55], v[160:163], v[176:179], v[52:55]
	v_mfma_f32_16x16x32_bf16 v[48:51], v[168:171], v[176:179], v[48:51]
	v_mfma_f32_16x16x32_bf16 v[36:39], v[160:163], v[184:187], v[36:39]
	v_mfma_f32_16x16x32_bf16 v[32:35], v[168:171], v[184:187], v[32:35]
	v_mfma_f32_16x16x32_bf16 v[20:23], v[160:163], v[198:201], v[20:23]
	v_mfma_f32_16x16x32_bf16 v[16:19], v[168:171], v[198:201], v[16:19]
	v_mfma_f32_16x16x32_bf16 v[4:7], v[160:163], v[222:225], v[4:7]
	v_mfma_f32_16x16x32_bf16 v[0:3], v[168:171], v[222:225], v[0:3]
	v_mfma_f32_16x16x32_bf16 v[52:55], v[164:167], v[180:183], v[52:55]
	v_mfma_f32_16x16x32_bf16 v[48:51], v[172:175], v[180:183], v[48:51]
	v_mfma_f32_16x16x32_bf16 v[36:39], v[164:167], v[188:191], v[36:39]
	v_mfma_f32_16x16x32_bf16 v[32:35], v[172:175], v[188:191], v[32:35]
	v_mfma_f32_16x16x32_bf16 v[20:23], v[164:167], v[218:221], v[20:23]
	v_mfma_f32_16x16x32_bf16 v[16:19], v[172:175], v[218:221], v[16:19]
	v_mfma_f32_16x16x32_bf16 v[4:7], v[164:167], v[226:229], v[4:7]
	v_mfma_f32_16x16x32_bf16 v[0:3], v[172:175], v[226:229], v[0:3]
	s_setprio 0
	s_barrier
	s_add_u32 s28, s28, 0x100
	s_addc_u32 s29, s29, 0
	s_add_u32 s48, s48, 0x100
	s_addc_u32 s49, s49, 0
	s_cmp_ge_i32 s82, s35
	s_mov_b32 s30, s82
	s_cbranch_scc0 .LBB0_1149
	s_movk_i32 s83, 0x7f

.LBB0_1226:
	s_add_i32 s26, s10, 2
	s_add_u32 s33, s0, 0x80
	s_addc_u32 s11, s1, 0
	s_add_i32 s35, 0, 0x10000
	s_cmp_eq_u32 s89, s10
	s_cselect_b32 s11, s87, s11
	s_cselect_b32 s10, s86, s33
	s_cselect_b32 s43, s97, s25
	s_cselect_b32 s42, s96, s24
	s_add_i32 s33, 0, 0x14000
	v_add_u32_e32 v140, s35, v229
	v_add_u32_e32 v156, s33, v229
	ds_read_b128 v[128:131], v140
	ds_read_b128 v[132:135], v140 offset:1024
	ds_read_b128 v[136:139], v140 offset:2048
	ds_read_b128 v[140:143], v140 offset:3072
	ds_read_b128 v[144:147], v156
	ds_read_b128 v[148:151], v156 offset:1024
	ds_read_b128 v[152:155], v156 offset:2048
	ds_read_b128 v[156:159], v156 offset:3072
	v_lshl_add_u64 v[190:191], s[0:1], 0, v[166:167]
	s_add_i32 m0, s29, 0xc000
	ds_read_b128 v[170:173], v230
	ds_read_b128 v[174:177], v230 offset:1024
	ds_read_b128 v[178:181], v230 offset:2048
	ds_read_b128 v[182:185], v230 offset:3072
	ds_read_b128 v[186:189], v230 offset:4096
	ds_read_b128 v[198:201], v230 offset:5120
	ds_read_b128 v[218:221], v230 offset:6144
	ds_read_b128 v[222:225], v230 offset:7168
	global_load_lds_dwordx4 v[190:191], off
	v_lshl_add_u64 v[190:191], s[0:1], 0, v[168:169]
	s_add_i32 m0, s29, 0xe000
	s_nop 0
	global_load_lds_dwordx4 v[190:191], off
	s_waitcnt vmcnt(8)
	s_waitcnt lgkmcnt(0)
	s_barrier
	s_setprio 1
	s_waitcnt lgkmcnt(0)
	v_mfma_f32_16x16x32_bf16 v[124:127], v[128:131], v[170:173], v[124:127]
	v_mfma_f32_16x16x32_bf16 v[120:123], v[136:139], v[170:173], v[120:123]
	v_mfma_f32_16x16x32_bf16 v[108:111], v[128:131], v[178:181], v[108:111]
	v_mfma_f32_16x16x32_bf16 v[104:107], v[136:139], v[178:181], v[104:107]
	v_mfma_f32_16x16x32_bf16 v[92:95], v[128:131], v[186:189], v[92:95]
	v_mfma_f32_16x16x32_bf16 v[88:91], v[136:139], v[186:189], v[88:91]
	v_mfma_f32_16x16x32_bf16 v[76:79], v[128:131], v[218:221], v[76:79]
	v_mfma_f32_16x16x32_bf16 v[72:75], v[136:139], v[218:221], v[72:75]
	v_mfma_f32_16x16x32_bf16 v[124:127], v[132:135], v[174:177], v[124:127]
	v_mfma_f32_16x16x32_bf16 v[120:123], v[140:143], v[174:177], v[120:123]
	v_mfma_f32_16x16x32_bf16 v[108:111], v[132:135], v[182:185], v[108:111]
	v_mfma_f32_16x16x32_bf16 v[104:107], v[140:143], v[182:185], v[104:107]
	v_mfma_f32_16x16x32_bf16 v[92:95], v[132:135], v[198:201], v[92:95]
	v_mfma_f32_16x16x32_bf16 v[88:91], v[140:143], v[198:201], v[88:91]
	v_mfma_f32_16x16x32_bf16 v[76:79], v[132:135], v[222:225], v[76:79]
	v_mfma_f32_16x16x32_bf16 v[72:75], v[140:143], v[222:225], v[72:75]
	v_mfma_f32_16x16x32_bf16 v[116:119], v[144:147], v[170:173], v[116:119]
	v_mfma_f32_16x16x32_bf16 v[112:115], v[152:155], v[170:173], v[112:115]
	v_mfma_f32_16x16x32_bf16 v[100:103], v[144:147], v[178:181], v[100:103]
	v_mfma_f32_16x16x32_bf16 v[96:99], v[152:155], v[178:181], v[96:99]
	v_mfma_f32_16x16x32_bf16 v[84:87], v[144:147], v[186:189], v[84:87]
	v_mfma_f32_16x16x32_bf16 v[80:83], v[152:155], v[186:189], v[80:83]
	v_mfma_f32_16x16x32_bf16 v[68:71], v[144:147], v[218:221], v[68:71]
	v_mfma_f32_16x16x32_bf16 v[64:67], v[152:155], v[218:221], v[64:67]
	v_mfma_f32_16x16x32_bf16 v[116:119], v[148:151], v[174:177], v[116:119]
	v_mfma_f32_16x16x32_bf16 v[112:115], v[156:159], v[174:177], v[112:115]
	v_mfma_f32_16x16x32_bf16 v[100:103], v[148:151], v[182:185], v[100:103]
	v_mfma_f32_16x16x32_bf16 v[96:99], v[156:159], v[182:185], v[96:99]
	v_mfma_f32_16x16x32_bf16 v[84:87], v[148:151], v[198:201], v[84:87]
	v_mfma_f32_16x16x32_bf16 v[80:83], v[156:159], v[198:201], v[80:83]
	v_mfma_f32_16x16x32_bf16 v[68:71], v[148:151], v[222:225], v[68:71]
	v_mfma_f32_16x16x32_bf16 v[64:67], v[156:159], v[222:225], v[64:67]
	s_setprio 0
	s_barrier
	s_add_i32 s35, s35, s28
	v_lshl_add_u64 v[190:191], s[42:43], 0, v[194:195]
	s_mov_b32 m0, s35
	ds_read_b128 v[170:173], v230 offset:16384
	ds_read_b128 v[174:177], v230 offset:17408
	ds_read_b128 v[178:181], v230 offset:18432
	ds_read_b128 v[182:185], v230 offset:19456
	ds_read_b128 v[186:189], v230 offset:20480
	ds_read_b128 v[198:201], v230 offset:21504
	ds_read_b128 v[218:221], v230 offset:22528
	ds_read_b128 v[222:225], v230 offset:23552
	global_load_lds_dwordx4 v[190:191], off
	s_add_i32 m0, s35, 0x2000
	v_lshl_add_u64 v[226:227], s[42:43], 0, v[160:161]
	s_add_u32 s42, s42, s8
	s_addc_u32 s43, s43, s9
	s_add_i32 s33, s33, s28
	global_load_lds_dwordx4 v[226:227], off
	v_lshl_add_u64 v[232:233], s[42:43], 0, v[194:195]
	s_mov_b32 m0, s33
	v_lshl_add_u64 v[234:235], s[42:43], 0, v[160:161]
	global_load_lds_dwordx4 v[232:233], off
	s_add_i32 m0, s33, 0x2000
	v_lshl_add_u64 v[236:237], s[10:11], 0, v[164:165]
	global_load_lds_dwordx4 v[234:235], off
	s_mov_b32 m0, s29
	v_lshl_add_u64 v[238:239], s[10:11], 0, v[162:163]
	global_load_lds_dwordx4 v[236:237], off
	s_mov_b32 m0, s30
	s_nop 0
	global_load_lds_dwordx4 v[238:239], off
	s_waitcnt vmcnt(8)
	s_waitcnt lgkmcnt(0)
	s_barrier
	s_setprio 1
	s_waitcnt lgkmcnt(0)
	v_mfma_f32_16x16x32_bf16 v[60:63], v[128:131], v[170:173], v[60:63]
	v_mfma_f32_16x16x32_bf16 v[56:59], v[136:139], v[170:173], v[56:59]
	v_mfma_f32_16x16x32_bf16 v[44:47], v[128:131], v[178:181], v[44:47]
	v_mfma_f32_16x16x32_bf16 v[40:43], v[136:139], v[178:181], v[40:43]
	v_mfma_f32_16x16x32_bf16 v[28:31], v[128:131], v[186:189], v[28:31]
	v_mfma_f32_16x16x32_bf16 v[24:27], v[136:139], v[186:189], v[24:27]
	v_mfma_f32_16x16x32_bf16 v[12:15], v[128:131], v[218:221], v[12:15]
	v_mfma_f32_16x16x32_bf16 v[8:11], v[136:139], v[218:221], v[8:11]
	v_mfma_f32_16x16x32_bf16 v[60:63], v[132:135], v[174:177], v[60:63]
	v_mfma_f32_16x16x32_bf16 v[56:59], v[140:143], v[174:177], v[56:59]
	v_mfma_f32_16x16x32_bf16 v[44:47], v[132:135], v[182:185], v[44:47]
	v_mfma_f32_16x16x32_bf16 v[40:43], v[140:143], v[182:185], v[40:43]
	v_mfma_f32_16x16x32_bf16 v[28:31], v[132:135], v[198:201], v[28:31]
	v_mfma_f32_16x16x32_bf16 v[24:27], v[140:143], v[198:201], v[24:27]
	v_mfma_f32_16x16x32_bf16 v[12:15], v[132:135], v[222:225], v[12:15]
	v_mfma_f32_16x16x32_bf16 v[8:11], v[140:143], v[222:225], v[8:11]
	v_mfma_f32_16x16x32_bf16 v[52:55], v[144:147], v[170:173], v[52:55]
	v_mfma_f32_16x16x32_bf16 v[48:51], v[152:155], v[170:173], v[48:51]
	v_mfma_f32_16x16x32_bf16 v[36:39], v[144:147], v[178:181], v[36:39]
	v_mfma_f32_16x16x32_bf16 v[32:35], v[152:155], v[178:181], v[32:35]
	v_mfma_f32_16x16x32_bf16 v[20:23], v[144:147], v[186:189], v[20:23]
	v_mfma_f32_16x16x32_bf16 v[16:19], v[152:155], v[186:189], v[16:19]
	v_mfma_f32_16x16x32_bf16 v[4:7], v[144:147], v[218:221], v[4:7]
	v_mfma_f32_16x16x32_bf16 v[0:3], v[152:155], v[218:221], v[0:3]
	v_mfma_f32_16x16x32_bf16 v[52:55], v[148:151], v[174:177], v[52:55]
	v_mfma_f32_16x16x32_bf16 v[48:51], v[156:159], v[174:177], v[48:51]
	v_mfma_f32_16x16x32_bf16 v[36:39], v[148:151], v[182:185], v[36:39]
	v_mfma_f32_16x16x32_bf16 v[32:35], v[156:159], v[182:185], v[32:35]
	v_mfma_f32_16x16x32_bf16 v[20:23], v[148:151], v[198:201], v[20:23]
	v_mfma_f32_16x16x32_bf16 v[16:19], v[156:159], v[198:201], v[16:19]
	v_mfma_f32_16x16x32_bf16 v[4:7], v[148:151], v[222:225], v[4:7]
	v_mfma_f32_16x16x32_bf16 v[0:3], v[156:159], v[222:225], v[0:3]
	s_setprio 0
	s_barrier
	s_add_i32 s33, 0, 0x18000
	s_add_i32 s35, 0, 0x1c000
	v_add_u32_e32 v140, s33, v229
	v_add_u32_e32 v156, s35, v229
	ds_read_b128 v[128:131], v140
	ds_read_b128 v[132:135], v140 offset:1024
	ds_read_b128 v[136:139], v140 offset:2048
	ds_read_b128 v[140:143], v140 offset:3072
	ds_read_b128 v[144:147], v156
	ds_read_b128 v[148:151], v156 offset:1024
	ds_read_b128 v[152:155], v156 offset:2048
	ds_read_b128 v[156:159], v156 offset:3072
	s_add_u32 s10, s10, s8
	s_addc_u32 s11, s11, s9
	s_mov_b32 m0, s31
	v_lshl_add_u64 v[240:241], s[10:11], 0, v[164:165]
	ds_read_b128 v[170:173], v230 offset:32768
	ds_read_b128 v[174:177], v230 offset:33792
	ds_read_b128 v[178:181], v230 offset:34816
	ds_read_b128 v[182:185], v230 offset:35840
	ds_read_b128 v[186:189], v230 offset:36864
	ds_read_b128 v[198:201], v230 offset:37888
	ds_read_b128 v[218:221], v230 offset:38912
	ds_read_b128 v[222:225], v230 offset:39936
	global_load_lds_dwordx4 v[240:241], off
	v_lshl_add_u64 v[240:241], s[10:11], 0, v[162:163]
	s_mov_b32 m0, s48
	s_nop 0
	global_load_lds_dwordx4 v[240:241], off
	s_waitcnt vmcnt(8)
	s_waitcnt lgkmcnt(0)
	s_barrier
	s_setprio 1
	s_waitcnt lgkmcnt(0)
	v_mfma_f32_16x16x32_bf16 v[124:127], v[128:131], v[170:173], v[124:127]
	v_mfma_f32_16x16x32_bf16 v[120:123], v[136:139], v[170:173], v[120:123]
	v_mfma_f32_16x16x32_bf16 v[108:111], v[128:131], v[178:181], v[108:111]
	v_mfma_f32_16x16x32_bf16 v[104:107], v[136:139], v[178:181], v[104:107]
	v_mfma_f32_16x16x32_bf16 v[92:95], v[128:131], v[186:189], v[92:95]
	v_mfma_f32_16x16x32_bf16 v[88:91], v[136:139], v[186:189], v[88:91]
	v_mfma_f32_16x16x32_bf16 v[76:79], v[128:131], v[218:221], v[76:79]
	v_mfma_f32_16x16x32_bf16 v[72:75], v[136:139], v[218:221], v[72:75]
	v_mfma_f32_16x16x32_bf16 v[124:127], v[132:135], v[174:177], v[124:127]
	v_mfma_f32_16x16x32_bf16 v[120:123], v[140:143], v[174:177], v[120:123]
	v_mfma_f32_16x16x32_bf16 v[108:111], v[132:135], v[182:185], v[108:111]
	v_mfma_f32_16x16x32_bf16 v[104:107], v[140:143], v[182:185], v[104:107]
	v_mfma_f32_16x16x32_bf16 v[92:95], v[132:135], v[198:201], v[92:95]
	v_mfma_f32_16x16x32_bf16 v[88:91], v[140:143], v[198:201], v[88:91]
	v_mfma_f32_16x16x32_bf16 v[76:79], v[132:135], v[222:225], v[76:79]
	v_mfma_f32_16x16x32_bf16 v[72:75], v[140:143], v[222:225], v[72:75]
	v_mfma_f32_16x16x32_bf16 v[116:119], v[144:147], v[170:173], v[116:119]
	v_mfma_f32_16x16x32_bf16 v[112:115], v[152:155], v[170:173], v[112:115]
	v_mfma_f32_16x16x32_bf16 v[100:103], v[144:147], v[178:181], v[100:103]
	v_mfma_f32_16x16x32_bf16 v[96:99], v[152:155], v[178:181], v[96:99]
	v_mfma_f32_16x16x32_bf16 v[84:87], v[144:147], v[186:189], v[84:87]
	v_mfma_f32_16x16x32_bf16 v[80:83], v[152:155], v[186:189], v[80:83]
	v_mfma_f32_16x16x32_bf16 v[68:71], v[144:147], v[218:221], v[68:71]
	v_mfma_f32_16x16x32_bf16 v[64:67], v[152:155], v[218:221], v[64:67]
	v_mfma_f32_16x16x32_bf16 v[116:119], v[148:151], v[174:177], v[116:119]
	v_mfma_f32_16x16x32_bf16 v[112:115], v[156:159], v[174:177], v[112:115]
	v_mfma_f32_16x16x32_bf16 v[100:103], v[148:151], v[182:185], v[100:103]
	v_mfma_f32_16x16x32_bf16 v[96:99], v[156:159], v[182:185], v[96:99]
	v_mfma_f32_16x16x32_bf16 v[84:87], v[148:151], v[198:201], v[84:87]
	v_mfma_f32_16x16x32_bf16 v[80:83], v[156:159], v[198:201], v[80:83]
	v_mfma_f32_16x16x32_bf16 v[68:71], v[148:151], v[222:225], v[68:71]
	v_mfma_f32_16x16x32_bf16 v[64:67], v[156:159], v[222:225], v[64:67]
	s_setprio 0
	s_barrier
	s_add_i32 s10, s33, s28
	v_lshl_add_u64 v[190:191], v[190:191], 0, s[38:39]
	s_mov_b32 m0, s10
	ds_read_b128 v[170:173], v230 offset:49152
	ds_read_b128 v[174:177], v230 offset:50176
	ds_read_b128 v[178:181], v230 offset:51200
	ds_read_b128 v[182:185], v230 offset:52224
	ds_read_b128 v[186:189], v230 offset:53248
	ds_read_b128 v[198:201], v230 offset:54272
	ds_read_b128 v[218:221], v230 offset:55296
	ds_read_b128 v[222:225], v230 offset:56320
	global_load_lds_dwordx4 v[190:191], off
	v_lshl_add_u64 v[190:191], v[226:227], 0, s[38:39]
	s_add_i32 m0, s10, 0x2000
	s_add_i32 s10, s35, s28
	global_load_lds_dwordx4 v[190:191], off
	v_lshl_add_u64 v[190:191], v[232:233], 0, s[38:39]
	s_mov_b32 m0, s10
	s_nop 0
	global_load_lds_dwordx4 v[190:191], off
	v_lshl_add_u64 v[190:191], v[234:235], 0, s[38:39]
	s_add_i32 m0, s10, 0x2000
	s_nop 0
	global_load_lds_dwordx4 v[190:191], off
	v_lshl_add_u64 v[190:191], v[236:237], 0, s[38:39]
	s_mov_b32 m0, s55
	s_nop 0
	global_load_lds_dwordx4 v[190:191], off
	v_lshl_add_u64 v[190:191], v[238:239], 0, s[38:39]
	s_mov_b32 m0, s88
	s_nop 0
	global_load_lds_dwordx4 v[190:191], off
	s_waitcnt vmcnt(8)
	s_waitcnt lgkmcnt(0)
	s_barrier
	s_setprio 1
	s_waitcnt lgkmcnt(0)
	v_mfma_f32_16x16x32_bf16 v[60:63], v[128:131], v[170:173], v[60:63]
	v_mfma_f32_16x16x32_bf16 v[56:59], v[136:139], v[170:173], v[56:59]
	v_mfma_f32_16x16x32_bf16 v[44:47], v[128:131], v[178:181], v[44:47]
	v_mfma_f32_16x16x32_bf16 v[40:43], v[136:139], v[178:181], v[40:43]
	v_mfma_f32_16x16x32_bf16 v[28:31], v[128:131], v[186:189], v[28:31]
	v_mfma_f32_16x16x32_bf16 v[24:27], v[136:139], v[186:189], v[24:27]
	v_mfma_f32_16x16x32_bf16 v[12:15], v[128:131], v[218:221], v[12:15]
	v_mfma_f32_16x16x32_bf16 v[8:11], v[136:139], v[218:221], v[8:11]
	v_mfma_f32_16x16x32_bf16 v[60:63], v[132:135], v[174:177], v[60:63]
	v_mfma_f32_16x16x32_bf16 v[56:59], v[140:143], v[174:177], v[56:59]
	v_mfma_f32_16x16x32_bf16 v[44:47], v[132:135], v[182:185], v[44:47]
	v_mfma_f32_16x16x32_bf16 v[40:43], v[140:143], v[182:185], v[40:43]
	v_mfma_f32_16x16x32_bf16 v[28:31], v[132:135], v[198:201], v[28:31]
	v_mfma_f32_16x16x32_bf16 v[24:27], v[140:143], v[198:201], v[24:27]
	v_mfma_f32_16x16x32_bf16 v[12:15], v[132:135], v[222:225], v[12:15]
	v_mfma_f32_16x16x32_bf16 v[8:11], v[140:143], v[222:225], v[8:11]
	v_mfma_f32_16x16x32_bf16 v[52:55], v[144:147], v[170:173], v[52:55]
	v_mfma_f32_16x16x32_bf16 v[48:51], v[152:155], v[170:173], v[48:51]
	v_mfma_f32_16x16x32_bf16 v[36:39], v[144:147], v[178:181], v[36:39]
	v_mfma_f32_16x16x32_bf16 v[32:35], v[152:155], v[178:181], v[32:35]
	v_mfma_f32_16x16x32_bf16 v[20:23], v[144:147], v[186:189], v[20:23]
	v_mfma_f32_16x16x32_bf16 v[16:19], v[152:155], v[186:189], v[16:19]
	v_mfma_f32_16x16x32_bf16 v[4:7], v[144:147], v[218:221], v[4:7]
	v_mfma_f32_16x16x32_bf16 v[0:3], v[152:155], v[218:221], v[0:3]
	v_mfma_f32_16x16x32_bf16 v[52:55], v[148:151], v[174:177], v[52:55]
	v_mfma_f32_16x16x32_bf16 v[48:51], v[156:159], v[174:177], v[48:51]
	v_mfma_f32_16x16x32_bf16 v[36:39], v[148:151], v[182:185], v[36:39]
	v_mfma_f32_16x16x32_bf16 v[32:35], v[156:159], v[182:185], v[32:35]
	v_mfma_f32_16x16x32_bf16 v[20:23], v[148:151], v[198:201], v[20:23]
	v_mfma_f32_16x16x32_bf16 v[16:19], v[156:159], v[198:201], v[16:19]
	v_mfma_f32_16x16x32_bf16 v[4:7], v[148:151], v[222:225], v[4:7]
	v_mfma_f32_16x16x32_bf16 v[0:3], v[156:159], v[222:225], v[0:3]
	s_setprio 0
	s_barrier
	s_add_u32 s0, s0, 0x100
	s_addc_u32 s1, s1, 0
	s_add_u32 s24, s24, 0x100
	s_addc_u32 s25, s25, 0
	s_cmp_ge_i32 s26, s50
	s_mov_b32 s10, s26
	s_cbranch_scc0 .LBB0_1226
